# attention dual job: tile 0's merge and normalisation arithmetic spread over tile 1's V steps, its output stores issued after the last V step
# baseline (speedup 1.0000x reference)
.Latt_noedge_4:
	s_nop 1
	v_max3_f32 v186, v36, v37, v38
	v_max3_f32 v186, v186, v39, v40
	v_max3_f32 v186, v186, v41, v42
	v_max3_f32 v186, v186, v43, v44
	v_max3_f32 v186, v186, v45, v46
	v_max3_f32 v186, v186, v47, v48
	v_max3_f32 v186, v186, v49, v50
	v_max3_f32 v186, v186, v51, v52
	v_max3_f32 v186, v186, v53, v54
	v_max3_f32 v186, v186, v55, v56
	v_max3_f32 v186, v186, v57, v58
	v_max3_f32 v186, v186, v59, v60
	v_max3_f32 v186, v186, v61, v62
	v_max3_f32 v186, v186, v63, v64
	v_max3_f32 v186, v186, v65, v66
	v_max3_f32 v186, v186, v67, v68
	v_max3_f32 v186, v186, v69, v70
	v_max_f32_e32 v186, v186, v71
	v_mov_b32_e32 v146, v186
	s_nop 1
	v_permlane16_swap_b32_e32 v186, v146
	v_max_f32_e32 v186, v186, v146
	v_mov_b32_e32 v146, v186
	s_nop 1
	v_permlane32_swap_b32_e32 v186, v146
	v_max_f32_e32 v186, v186, v146
	v_pk_add_f32 v[36:37], v[36:37], v[186:187] op_sel_hi:[1,0] neg_lo:[0,1] neg_hi:[0,1]
	v_pk_add_f32 v[38:39], v[38:39], v[186:187] op_sel_hi:[1,0] neg_lo:[0,1] neg_hi:[0,1]
	v_pk_add_f32 v[40:41], v[40:41], v[186:187] op_sel_hi:[1,0] neg_lo:[0,1] neg_hi:[0,1]
	v_pk_add_f32 v[42:43], v[42:43], v[186:187] op_sel_hi:[1,0] neg_lo:[0,1] neg_hi:[0,1]
	v_exp_f32_e32 v36, v36
	v_exp_f32_e32 v37, v37
	v_exp_f32_e32 v38, v38
	v_exp_f32_e32 v39, v39
	v_pk_add_f32 v[44:45], v[44:45], v[186:187] op_sel_hi:[1,0] neg_lo:[0,1] neg_hi:[0,1]
	v_pk_add_f32 v[46:47], v[46:47], v[186:187] op_sel_hi:[1,0] neg_lo:[0,1] neg_hi:[0,1]
	v_exp_f32_e32 v40, v40
	v_exp_f32_e32 v41, v41
	v_exp_f32_e32 v42, v42
	v_exp_f32_e32 v43, v43
	v_pk_add_f32 v[48:49], v[48:49], v[186:187] op_sel_hi:[1,0] neg_lo:[0,1] neg_hi:[0,1]
	v_pk_add_f32 v[50:51], v[50:51], v[186:187] op_sel_hi:[1,0] neg_lo:[0,1] neg_hi:[0,1]
	v_exp_f32_e32 v44, v44
	v_exp_f32_e32 v45, v45
	v_exp_f32_e32 v46, v46
	v_exp_f32_e32 v47, v47
	v_pk_add_f32 v[52:53], v[52:53], v[186:187] op_sel_hi:[1,0] neg_lo:[0,1] neg_hi:[0,1]
	v_pk_add_f32 v[54:55], v[54:55], v[186:187] op_sel_hi:[1,0] neg_lo:[0,1] neg_hi:[0,1]
	v_exp_f32_e32 v48, v48
	v_exp_f32_e32 v49, v49
	v_exp_f32_e32 v50, v50
	v_exp_f32_e32 v51, v51
	v_pk_add_f32 v[56:57], v[56:57], v[186:187] op_sel_hi:[1,0] neg_lo:[0,1] neg_hi:[0,1]
	v_pk_add_f32 v[58:59], v[58:59], v[186:187] op_sel_hi:[1,0] neg_lo:[0,1] neg_hi:[0,1]
	v_exp_f32_e32 v52, v52
	v_exp_f32_e32 v53, v53
	v_exp_f32_e32 v54, v54
	v_exp_f32_e32 v55, v55
	v_pk_add_f32 v[60:61], v[60:61], v[186:187] op_sel_hi:[1,0] neg_lo:[0,1] neg_hi:[0,1]
	v_pk_add_f32 v[62:63], v[62:63], v[186:187] op_sel_hi:[1,0] neg_lo:[0,1] neg_hi:[0,1]
	v_exp_f32_e32 v56, v56
	v_exp_f32_e32 v57, v57
	v_exp_f32_e32 v58, v58
	v_exp_f32_e32 v59, v59
	v_pk_add_f32 v[64:65], v[64:65], v[186:187] op_sel_hi:[1,0] neg_lo:[0,1] neg_hi:[0,1]
	v_pk_add_f32 v[66:67], v[66:67], v[186:187] op_sel_hi:[1,0] neg_lo:[0,1] neg_hi:[0,1]
	v_exp_f32_e32 v60, v60
	v_exp_f32_e32 v61, v61
	v_exp_f32_e32 v62, v62
	v_exp_f32_e32 v63, v63
	v_pk_add_f32 v[68:69], v[68:69], v[186:187] op_sel_hi:[1,0] neg_lo:[0,1] neg_hi:[0,1]
	v_pk_add_f32 v[70:71], v[70:71], v[186:187] op_sel_hi:[1,0] neg_lo:[0,1] neg_hi:[0,1]
	v_exp_f32_e32 v64, v64
	v_exp_f32_e32 v65, v65
	v_exp_f32_e32 v66, v66
	v_exp_f32_e32 v67, v67
	v_exp_f32_e32 v68, v68
	v_exp_f32_e32 v69, v69
	v_exp_f32_e32 v70, v70
	v_exp_f32_e32 v71, v71
	s_nop 0
	v_pk_add_f32 v[146:147], v[36:37], v[38:39]
	v_pk_add_f32 v[148:149], v[40:41], v[42:43]
	v_pk_add_f32 v[146:147], v[146:147], v[44:45]
	v_pk_add_f32 v[148:149], v[148:149], v[46:47]
	v_pk_add_f32 v[146:147], v[146:147], v[48:49]
	v_pk_add_f32 v[148:149], v[148:149], v[50:51]
	v_pk_add_f32 v[146:147], v[146:147], v[52:53]
	v_pk_add_f32 v[148:149], v[148:149], v[54:55]
	v_pk_add_f32 v[146:147], v[146:147], v[56:57]
	v_pk_add_f32 v[148:149], v[148:149], v[58:59]
	v_pk_add_f32 v[146:147], v[146:147], v[60:61]
	v_pk_add_f32 v[148:149], v[148:149], v[62:63]
	v_pk_add_f32 v[146:147], v[146:147], v[64:65]
	v_pk_add_f32 v[148:149], v[148:149], v[66:67]
	v_pk_add_f32 v[146:147], v[146:147], v[68:69]
	v_pk_add_f32 v[148:149], v[148:149], v[70:71]
	s_nop 0
	v_pk_add_f32 v[146:147], v[146:147], v[148:149]
	s_nop 0
	v_add_f32_e32 v187, v146, v147
	v_cvt_pk_bf16_f32 v36, v36, v37
	v_cvt_pk_bf16_f32 v37, v38, v39
	v_cvt_pk_bf16_f32 v40, v40, v41
	v_cvt_pk_bf16_f32 v41, v42, v43
	v_cvt_pk_bf16_f32 v44, v44, v45
	v_cvt_pk_bf16_f32 v45, v46, v47
	v_cvt_pk_bf16_f32 v48, v48, v49
	v_cvt_pk_bf16_f32 v49, v50, v51
	v_cvt_pk_bf16_f32 v52, v52, v53
	v_cvt_pk_bf16_f32 v53, v54, v55
	v_cvt_pk_bf16_f32 v56, v56, v57
	v_cvt_pk_bf16_f32 v57, v58, v59
	v_cvt_pk_bf16_f32 v60, v60, v61
	v_cvt_pk_bf16_f32 v61, v62, v63
	v_cvt_pk_bf16_f32 v64, v64, v65
	v_cvt_pk_bf16_f32 v65, v66, v67
	v_cvt_pk_bf16_f32 v68, v68, v69
	v_cvt_pk_bf16_f32 v69, v70, v71
	v_mov_b32_e32 v146, v187
	s_nop 1
	v_permlane16_swap_b32_e32 v187, v146
	v_add_f32_e32 v187, v187, v146
	v_mov_b32_e32 v146, v187
	s_nop 1
	v_permlane32_swap_b32_e32 v187, v146
	v_add_f32_e32 v187, v187, v146
	s_waitcnt lgkmcnt(0)
	s_add_i32 s93, s76, 64
	s_mov_b32 m0, s16
	v_add_u32_e32 v164, s93, v231
	v_med3_i32 v164, v164, 0, s40
	v_lshl_or_b32 v164, v164, 7, v222
	global_load_lds_dwordx4 v164, s[24:25]
	s_add_i32 m0, s16, 0x400
	v_add_u32_e32 v165, s93, v232
	v_med3_i32 v165, v165, 0, s40
	v_lshl_or_b32 v165, v165, 7, v222
	global_load_lds_dwordx4 v165, s[24:25]
	s_waitcnt vmcnt(8)
	v_add_u32_e32 v154, s12, v225
	v_add_u32_e32 v155, s12, v226
	v_add_u32_e32 v156, s12, v227
	v_add_u32_e32 v157, s12, v228
	ds_read_b64_tr_b16 v[202:203], v154
	ds_read_b64_tr_b16 v[204:205], v155
	ds_read_b64_tr_b16 v[206:207], v156
	ds_read_b64_tr_b16 v[208:209], v157
	v_mfma_f32_16x16x16_bf16 v[96:99], v[88:89], v[0:1], 0
	v_mfma_f32_16x16x16_bf16 v[100:103], v[90:91], v[0:1], 0
	v_mfma_f32_16x16x16_bf16 v[104:107], v[92:93], v[0:1], 0
	v_mfma_f32_16x16x16_bf16 v[108:111], v[94:95], v[0:1], 0
	s_waitcnt lgkmcnt(0)
	s_add_i32 s93, s76, 0x80
	s_mov_b32 m0, s12
	v_add_u32_e32 v164, s93, v231
	v_med3_i32 v164, v164, 0, s40
	v_lshl_or_b32 v164, v164, 7, v222
	global_load_lds_dwordx4 v164, s[24:25]
	s_add_i32 m0, s12, 0x400
	v_add_u32_e32 v165, s93, v232
	v_med3_i32 v165, v165, 0, s40
	v_lshl_or_b32 v165, v165, 7, v222
	global_load_lds_dwordx4 v165, s[24:25]
	s_waitcnt vmcnt(8)
	v_add_u32_e32 v154, s13, v225
	v_add_u32_e32 v155, s13, v226
	v_add_u32_e32 v156, s13, v227
	v_add_u32_e32 v157, s13, v228
	ds_read_b64_tr_b16 v[88:89], v154
	ds_read_b64_tr_b16 v[90:91], v155
	ds_read_b64_tr_b16 v[92:93], v156
	ds_read_b64_tr_b16 v[94:95], v157
	v_mfma_f32_16x16x16_bf16 v[96:99], v[202:203], v[4:5], v[96:99]
	v_mfma_f32_16x16x16_bf16 v[112:115], v[202:203], v[36:37], 0
	v_mfma_f32_16x16x16_bf16 v[100:103], v[204:205], v[4:5], v[100:103]
	v_mfma_f32_16x16x16_bf16 v[116:119], v[204:205], v[36:37], 0
	v_mfma_f32_16x16x16_bf16 v[104:107], v[206:207], v[4:5], v[104:107]
	v_mfma_f32_16x16x16_bf16 v[120:123], v[206:207], v[36:37], 0
	v_mfma_f32_16x16x16_bf16 v[108:111], v[208:209], v[4:5], v[108:111]
	v_mfma_f32_16x16x16_bf16 v[124:127], v[208:209], v[36:37], 0
	s_waitcnt lgkmcnt(0)
	s_add_i32 s93, s76, 0xc0
	s_mov_b32 m0, s13
	v_add_u32_e32 v164, s93, v231
	v_med3_i32 v164, v164, 0, s40
	v_lshl_or_b32 v164, v164, 7, v222
	global_load_lds_dwordx4 v164, s[24:25]
	s_add_i32 m0, s13, 0x400
	v_add_u32_e32 v165, s93, v232
	v_med3_i32 v165, v165, 0, s40
	v_lshl_or_b32 v165, v165, 7, v222
	global_load_lds_dwordx4 v165, s[24:25]
	s_waitcnt vmcnt(8)
	v_add_u32_e32 v154, s14, v225
	v_add_u32_e32 v155, s14, v226
	v_add_u32_e32 v156, s14, v227
	v_add_u32_e32 v157, s14, v228
	ds_read_b64_tr_b16 v[202:203], v154
	ds_read_b64_tr_b16 v[204:205], v155
	ds_read_b64_tr_b16 v[206:207], v156
	ds_read_b64_tr_b16 v[208:209], v157
	v_mfma_f32_16x16x16_bf16 v[96:99], v[88:89], v[8:9], v[96:99]
	v_mfma_f32_16x16x16_bf16 v[112:115], v[88:89], v[40:41], v[112:115]
	v_mfma_f32_16x16x16_bf16 v[100:103], v[90:91], v[8:9], v[100:103]
	v_mfma_f32_16x16x16_bf16 v[116:119], v[90:91], v[40:41], v[116:119]
	v_mfma_f32_16x16x16_bf16 v[104:107], v[92:93], v[8:9], v[104:107]
	v_mfma_f32_16x16x16_bf16 v[120:123], v[92:93], v[40:41], v[120:123]
	v_mfma_f32_16x16x16_bf16 v[108:111], v[94:95], v[8:9], v[108:111]
	v_mfma_f32_16x16x16_bf16 v[124:127], v[94:95], v[40:41], v[124:127]
	s_waitcnt lgkmcnt(0)
	s_add_i32 s93, s76, 0x100
	s_mov_b32 m0, s14
	v_add_u32_e32 v164, s93, v231
	v_med3_i32 v164, v164, 0, s40
	v_lshl_or_b32 v164, v164, 7, v222
	global_load_lds_dwordx4 v164, s[24:25]
	s_add_i32 m0, s14, 0x400
	v_add_u32_e32 v165, s93, v232
	v_med3_i32 v165, v165, 0, s40
	v_lshl_or_b32 v165, v165, 7, v222
	global_load_lds_dwordx4 v165, s[24:25]
	s_waitcnt vmcnt(8)
	v_add_u32_e32 v154, s15, v225
	v_add_u32_e32 v155, s15, v226
	v_add_u32_e32 v156, s15, v227
	v_add_u32_e32 v157, s15, v228
	ds_read_b64_tr_b16 v[88:89], v154
	ds_read_b64_tr_b16 v[90:91], v155
	ds_read_b64_tr_b16 v[92:93], v156
	ds_read_b64_tr_b16 v[94:95], v157
	v_mfma_f32_16x16x16_bf16 v[96:99], v[202:203], v[12:13], v[96:99]
	v_mfma_f32_16x16x16_bf16 v[112:115], v[202:203], v[44:45], v[112:115]
	v_mfma_f32_16x16x16_bf16 v[100:103], v[204:205], v[12:13], v[100:103]
	v_mfma_f32_16x16x16_bf16 v[116:119], v[204:205], v[44:45], v[116:119]
	v_mfma_f32_16x16x16_bf16 v[104:107], v[206:207], v[12:13], v[104:107]
	v_mfma_f32_16x16x16_bf16 v[120:123], v[206:207], v[44:45], v[120:123]
	v_mfma_f32_16x16x16_bf16 v[108:111], v[208:209], v[12:13], v[108:111]
	v_mfma_f32_16x16x16_bf16 v[124:127], v[208:209], v[44:45], v[124:127]
	s_waitcnt lgkmcnt(0)
	s_add_i32 s93, s76, 0x140
	s_mov_b32 m0, s15
	v_add_u32_e32 v164, s93, v231
	v_med3_i32 v164, v164, 0, s40
	v_lshl_or_b32 v164, v164, 7, v222
	global_load_lds_dwordx4 v164, s[24:25]
	s_add_i32 m0, s15, 0x400
	v_add_u32_e32 v165, s93, v232
	v_med3_i32 v165, v165, 0, s40
	v_lshl_or_b32 v165, v165, 7, v222
	global_load_lds_dwordx4 v165, s[24:25]
	s_waitcnt vmcnt(8)
	v_add_u32_e32 v154, s16, v225
	v_add_u32_e32 v155, s16, v226
	v_add_u32_e32 v156, s16, v227
	v_add_u32_e32 v157, s16, v228
	ds_read_b64_tr_b16 v[202:203], v154
	ds_read_b64_tr_b16 v[204:205], v155
	ds_read_b64_tr_b16 v[206:207], v156
	ds_read_b64_tr_b16 v[208:209], v157
	v_mfma_f32_16x16x16_bf16 v[96:99], v[88:89], v[16:17], v[96:99]
	v_mfma_f32_16x16x16_bf16 v[112:115], v[88:89], v[48:49], v[112:115]
	v_mfma_f32_16x16x16_bf16 v[100:103], v[90:91], v[16:17], v[100:103]
	v_mfma_f32_16x16x16_bf16 v[116:119], v[90:91], v[48:49], v[116:119]
	v_mfma_f32_16x16x16_bf16 v[104:107], v[92:93], v[16:17], v[104:107]
	v_mfma_f32_16x16x16_bf16 v[120:123], v[92:93], v[48:49], v[120:123]
	v_mfma_f32_16x16x16_bf16 v[108:111], v[94:95], v[16:17], v[108:111]
	v_mfma_f32_16x16x16_bf16 v[124:127], v[94:95], v[48:49], v[124:127]
	s_waitcnt lgkmcnt(0)
	s_add_i32 s93, s79, 0
	s_mov_b32 m0, s16
	v_add_u32_e32 v164, s93, v162
	v_lshl_or_b32 v164, v164, 7, v220
	global_load_lds_dwordx4 v164, s[18:19]
	s_add_i32 m0, s16, 0x400
	v_add_u32_e32 v165, s93, v163
	v_lshl_or_b32 v165, v165, 7, v221
	global_load_lds_dwordx4 v165, s[18:19]
	s_waitcnt vmcnt(8)
	v_add_u32_e32 v154, s12, v225
	v_add_u32_e32 v155, s12, v226
	v_add_u32_e32 v156, s12, v227
	v_add_u32_e32 v157, s12, v228
	ds_read_b64_tr_b16 v[88:89], v154
	ds_read_b64_tr_b16 v[90:91], v155
	ds_read_b64_tr_b16 v[92:93], v156
	ds_read_b64_tr_b16 v[94:95], v157
	v_mfma_f32_16x16x16_bf16 v[96:99], v[202:203], v[20:21], v[96:99]
	v_mfma_f32_16x16x16_bf16 v[112:115], v[202:203], v[52:53], v[112:115]
	v_mfma_f32_16x16x16_bf16 v[100:103], v[204:205], v[20:21], v[100:103]
	v_mfma_f32_16x16x16_bf16 v[116:119], v[204:205], v[52:53], v[116:119]
	v_mfma_f32_16x16x16_bf16 v[104:107], v[206:207], v[20:21], v[104:107]
	v_mfma_f32_16x16x16_bf16 v[120:123], v[206:207], v[52:53], v[120:123]
	v_mfma_f32_16x16x16_bf16 v[108:111], v[208:209], v[20:21], v[108:111]
	v_mfma_f32_16x16x16_bf16 v[124:127], v[208:209], v[52:53], v[124:127]
	s_waitcnt lgkmcnt(0)
	s_add_i32 s93, s79, 0xfffffc00
	s_mov_b32 m0, s12
	v_add_u32_e32 v164, s93, v162
	v_med3_i32 v164, v164, 0, s40
	v_lshl_or_b32 v164, v164, 7, v220
	global_load_lds_dwordx4 v164, s[20:21]
	s_add_i32 m0, s12, 0x400
	v_add_u32_e32 v165, s93, v163
	v_med3_i32 v165, v165, 0, s40
	v_lshl_or_b32 v165, v165, 7, v221
	global_load_lds_dwordx4 v165, s[20:21]
	s_waitcnt vmcnt(8)
	v_add_u32_e32 v154, s13, v225
	v_add_u32_e32 v155, s13, v226
	v_add_u32_e32 v156, s13, v227
	v_add_u32_e32 v157, s13, v228
	ds_read_b64_tr_b16 v[202:203], v154
	ds_read_b64_tr_b16 v[204:205], v155
	ds_read_b64_tr_b16 v[206:207], v156
	ds_read_b64_tr_b16 v[208:209], v157
	v_mfma_f32_16x16x16_bf16 v[96:99], v[88:89], v[24:25], v[96:99]
	v_mfma_f32_16x16x16_bf16 v[112:115], v[88:89], v[56:57], v[112:115]
	v_mfma_f32_16x16x16_bf16 v[100:103], v[90:91], v[24:25], v[100:103]
	v_mfma_f32_16x16x16_bf16 v[116:119], v[90:91], v[56:57], v[116:119]
	v_mfma_f32_16x16x16_bf16 v[104:107], v[92:93], v[24:25], v[104:107]
	v_mfma_f32_16x16x16_bf16 v[120:123], v[92:93], v[56:57], v[120:123]
	v_mfma_f32_16x16x16_bf16 v[108:111], v[94:95], v[24:25], v[108:111]
	v_mfma_f32_16x16x16_bf16 v[124:127], v[94:95], v[56:57], v[124:127]
	s_waitcnt lgkmcnt(0)
	s_add_i32 s93, s79, 0xfffffd00
	s_mov_b32 m0, s13
	v_add_u32_e32 v164, s93, v162
	v_med3_i32 v164, v164, 0, s40
	v_lshl_or_b32 v164, v164, 7, v220
	global_load_lds_dwordx4 v164, s[20:21]
	s_add_i32 m0, s13, 0x400
	v_add_u32_e32 v165, s93, v163
	v_med3_i32 v165, v165, 0, s40
	v_lshl_or_b32 v165, v165, 7, v221
	global_load_lds_dwordx4 v165, s[20:21]
	s_waitcnt vmcnt(8)
	v_add_u32_e32 v154, s14, v225
	v_add_u32_e32 v155, s14, v226
	v_add_u32_e32 v156, s14, v227
	v_add_u32_e32 v157, s14, v228
	ds_read_b64_tr_b16 v[88:89], v154
	ds_read_b64_tr_b16 v[90:91], v155
	ds_read_b64_tr_b16 v[92:93], v156
	ds_read_b64_tr_b16 v[94:95], v157
	v_mfma_f32_16x16x16_bf16 v[96:99], v[202:203], v[28:29], v[96:99]
	v_mfma_f32_16x16x16_bf16 v[112:115], v[202:203], v[60:61], v[112:115]
	v_mfma_f32_16x16x16_bf16 v[100:103], v[204:205], v[28:29], v[100:103]
	v_mfma_f32_16x16x16_bf16 v[116:119], v[204:205], v[60:61], v[116:119]
	v_mfma_f32_16x16x16_bf16 v[104:107], v[206:207], v[28:29], v[104:107]
	v_mfma_f32_16x16x16_bf16 v[120:123], v[206:207], v[60:61], v[120:123]
	v_mfma_f32_16x16x16_bf16 v[108:111], v[208:209], v[28:29], v[108:111]
	v_mfma_f32_16x16x16_bf16 v[124:127], v[208:209], v[60:61], v[124:127]
	s_waitcnt lgkmcnt(0)
	s_add_i32 s93, s79, 0xfffffe00
	s_mov_b32 m0, s14
	v_add_u32_e32 v164, s93, v162
	v_med3_i32 v164, v164, 0, s40
	v_lshl_or_b32 v164, v164, 7, v220
	global_load_lds_dwordx4 v164, s[20:21]
	s_add_i32 m0, s14, 0x400
	v_add_u32_e32 v165, s93, v163
	v_med3_i32 v165, v165, 0, s40
	v_lshl_or_b32 v165, v165, 7, v221
	global_load_lds_dwordx4 v165, s[20:21]
	s_waitcnt vmcnt(8)
	v_add_u32_e32 v154, s15, v225
	v_add_u32_e32 v155, s15, v226
	v_add_u32_e32 v156, s15, v227
	v_add_u32_e32 v157, s15, v228
	ds_read_b64_tr_b16 v[202:203], v154
	ds_read_b64_tr_b16 v[204:205], v155
	ds_read_b64_tr_b16 v[206:207], v156
	ds_read_b64_tr_b16 v[208:209], v157
	v_mfma_f32_16x16x16_bf16 v[96:99], v[88:89], v[32:33], v[96:99]
	v_mfma_f32_16x16x16_bf16 v[112:115], v[88:89], v[64:65], v[112:115]
	v_mfma_f32_16x16x16_bf16 v[100:103], v[90:91], v[32:33], v[100:103]
	v_mfma_f32_16x16x16_bf16 v[116:119], v[90:91], v[64:65], v[116:119]
	v_mfma_f32_16x16x16_bf16 v[104:107], v[92:93], v[32:33], v[104:107]
	v_mfma_f32_16x16x16_bf16 v[120:123], v[92:93], v[64:65], v[120:123]
	v_mfma_f32_16x16x16_bf16 v[108:111], v[94:95], v[32:33], v[108:111]
	v_mfma_f32_16x16x16_bf16 v[124:127], v[94:95], v[64:65], v[124:127]
	s_waitcnt lgkmcnt(0)
	s_add_i32 s93, s79, 0xffffff00
	s_mov_b32 m0, s15
	v_add_u32_e32 v164, s93, v162
	v_med3_i32 v164, v164, 0, s40
	v_lshl_or_b32 v164, v164, 7, v220
	global_load_lds_dwordx4 v164, s[20:21]
	s_add_i32 m0, s15, 0x400
	v_add_u32_e32 v165, s93, v163
	v_med3_i32 v165, v165, 0, s40
	v_lshl_or_b32 v165, v165, 7, v221
	global_load_lds_dwordx4 v165, s[20:21]
	v_mfma_f32_16x16x16_bf16 v[112:115], v[202:203], v[68:69], v[112:115]
	v_mfma_f32_16x16x16_bf16 v[116:119], v[204:205], v[68:69], v[116:119]
	v_mfma_f32_16x16x16_bf16 v[120:123], v[206:207], v[68:69], v[120:123]
	v_mfma_f32_16x16x16_bf16 v[124:127], v[208:209], v[68:69], v[124:127]
	s_waitcnt lgkmcnt(0)
	v_max_f32_e32 v146, v144, v184
	v_sub_f32_e32 v148, v144, v146
	v_sub_f32_e32 v150, v184, v146
	v_exp_f32_e32 v148, v148
	v_exp_f32_e32 v150, v150
	v_mov_b32_e32 v184, v146
	v_mul_f32_e32 v185, v185, v150
	v_fmac_f32_e32 v185, v145, v148
	v_pk_mul_f32 v[96:97], v[150:151], v[96:97] op_sel_hi:[0,1]
	v_pk_mul_f32 v[98:99], v[150:151], v[98:99] op_sel_hi:[0,1]
	v_pk_mul_f32 v[100:101], v[150:151], v[100:101] op_sel_hi:[0,1]
	v_pk_mul_f32 v[102:103], v[150:151], v[102:103] op_sel_hi:[0,1]
	v_pk_mul_f32 v[104:105], v[150:151], v[104:105] op_sel_hi:[0,1]
	v_pk_mul_f32 v[106:107], v[150:151], v[106:107] op_sel_hi:[0,1]
	v_pk_mul_f32 v[108:109], v[150:151], v[108:109] op_sel_hi:[0,1]
	v_pk_mul_f32 v[110:111], v[150:151], v[110:111] op_sel_hi:[0,1]
	v_pk_fma_f32 v[96:97], v[148:149], v[128:129], v[96:97] op_sel_hi:[0,1,1]
	v_pk_fma_f32 v[98:99], v[148:149], v[130:131], v[98:99] op_sel_hi:[0,1,1]
	v_pk_fma_f32 v[100:101], v[148:149], v[132:133], v[100:101] op_sel_hi:[0,1,1]
	v_pk_fma_f32 v[102:103], v[148:149], v[134:135], v[102:103] op_sel_hi:[0,1,1]
	v_pk_fma_f32 v[104:105], v[148:149], v[136:137], v[104:105] op_sel_hi:[0,1,1]
	v_pk_fma_f32 v[106:107], v[148:149], v[138:139], v[106:107] op_sel_hi:[0,1,1]
	v_pk_fma_f32 v[108:109], v[148:149], v[140:141], v[108:109] op_sel_hi:[0,1,1]
	v_pk_fma_f32 v[110:111], v[148:149], v[142:143], v[110:111] op_sel_hi:[0,1,1]
	s_and_saveexec_b64 s[80:81], s[74:75]
	ds_write_b64 v194, v[184:185]
	s_mov_b64 exec, s[80:81]
	ds_write_b128 v190, v[96:99]
	ds_write_b128 v191, v[100:103]
	ds_write_b128 v192, v[104:107]
	ds_write_b128 v193, v[108:111]
	s_waitcnt lgkmcnt(0)
	v_max_f32_e32 v146, v182, v186
	v_sub_f32_e32 v148, v182, v146
	v_sub_f32_e32 v150, v186, v146
	v_exp_f32_e32 v148, v148
	v_exp_f32_e32 v150, v150
	v_mov_b32_e32 v186, v146
	v_mul_f32_e32 v187, v187, v150
	v_fmac_f32_e32 v187, v183, v148
	v_pk_mul_f32 v[112:113], v[150:151], v[112:113] op_sel_hi:[0,1]
	v_pk_mul_f32 v[114:115], v[150:151], v[114:115] op_sel_hi:[0,1]
	v_pk_mul_f32 v[116:117], v[150:151], v[116:117] op_sel_hi:[0,1]
	v_pk_mul_f32 v[118:119], v[150:151], v[118:119] op_sel_hi:[0,1]
	v_pk_mul_f32 v[120:121], v[150:151], v[120:121] op_sel_hi:[0,1]
	v_pk_mul_f32 v[122:123], v[150:151], v[122:123] op_sel_hi:[0,1]
	v_pk_mul_f32 v[124:125], v[150:151], v[124:125] op_sel_hi:[0,1]
	v_pk_mul_f32 v[126:127], v[150:151], v[126:127] op_sel_hi:[0,1]
	v_pk_fma_f32 v[112:113], v[148:149], v[166:167], v[112:113] op_sel_hi:[0,1,1]
	v_pk_fma_f32 v[114:115], v[148:149], v[168:169], v[114:115] op_sel_hi:[0,1,1]
	v_pk_fma_f32 v[116:117], v[148:149], v[170:171], v[116:117] op_sel_hi:[0,1,1]
	v_pk_fma_f32 v[118:119], v[148:149], v[172:173], v[118:119] op_sel_hi:[0,1,1]
	v_pk_fma_f32 v[120:121], v[148:149], v[174:175], v[120:121] op_sel_hi:[0,1,1]
	v_pk_fma_f32 v[122:123], v[148:149], v[176:177], v[122:123] op_sel_hi:[0,1,1]
	v_pk_fma_f32 v[124:125], v[148:149], v[178:179], v[124:125] op_sel_hi:[0,1,1]
	v_pk_fma_f32 v[126:127], v[148:149], v[180:181], v[126:127] op_sel_hi:[0,1,1]
	s_and_saveexec_b64 s[80:81], s[74:75]
	ds_write_b64 v199, v[186:187]
	s_mov_b64 exec, s[80:81]
	ds_write_b128 v195, v[112:115]
	ds_write_b128 v196, v[116:119]
	ds_write_b128 v197, v[120:123]
	ds_write_b128 v198, v[124:127]
	s_waitcnt lgkmcnt(0)
	s_barrier
	s_add_i32 s76, s38, s84
	s_add_i32 s79, s39, s82
	v_lshlrev_b32_e32 v231, 4, v218
	v_add_u32_e32 v232, 8, v218
	v_lshlrev_b32_e32 v232, 4, v232
	v_lshlrev_b32_e32 v162, 0, v218
	v_add_u32_e32 v163, 8, v218
	v_lshlrev_b32_e32 v163, 0, v163
	s_add_i32 s8, s38, s85
	s_waitcnt vmcnt(8)
	v_add_u32_e32 v154, s16, v223
	v_add_u32_e32 v155, s16, v224
	ds_read_b128 v[72:75], v154
	ds_read_b128 v[76:79], v155
	s_waitcnt lgkmcnt(0)
	s_add_i32 s93, s76, 0
	s_mov_b32 m0, s16
	v_add_u32_e32 v164, s93, v231
	v_med3_i32 v164, v164, 0, s40
	v_lshl_or_b32 v164, v164, 7, v220
	global_load_lds_dwordx4 v164, s[20:21]
	s_add_i32 m0, s16, 0x400
	v_add_u32_e32 v165, s93, v232
	v_med3_i32 v165, v165, 0, s40
	v_lshl_or_b32 v165, v165, 7, v221
	global_load_lds_dwordx4 v165, s[20:21]
	s_waitcnt vmcnt(8)
	v_add_u32_e32 v154, s12, v223
	v_add_u32_e32 v155, s12, v224
	ds_read_b128 v[202:205], v154
	ds_read_b128 v[206:209], v155
	s_waitcnt lgkmcnt(0)
	s_add_i32 s93, s76, 0x100
	s_mov_b32 m0, s12
	v_add_u32_e32 v164, s93, v231
	v_med3_i32 v164, v164, 0, s40
	v_lshl_or_b32 v164, v164, 7, v220
	global_load_lds_dwordx4 v164, s[20:21]
	s_add_i32 m0, s12, 0x400
	v_add_u32_e32 v165, s93, v232
	v_med3_i32 v165, v165, 0, s40
	v_lshl_or_b32 v165, v165, 7, v221
	global_load_lds_dwordx4 v165, s[20:21]
	s_waitcnt vmcnt(8)
	v_add_u32_e32 v154, s13, v223
	v_add_u32_e32 v155, s13, v224
	ds_read_b128 v[88:91], v154
	ds_read_b128 v[92:95], v155
	v_mfma_f32_16x16x32_bf16 v[0:3], v[202:205], v[72:75], 0
	v_mfma_f32_16x16x32_bf16 v[0:3], v[206:209], v[76:79], v[0:3]
	s_waitcnt lgkmcnt(0)
	s_add_i32 s93, s76, 0x200
	s_mov_b32 m0, s13
	v_add_u32_e32 v164, s93, v231
	v_med3_i32 v164, v164, 0, s40
	v_lshl_or_b32 v164, v164, 7, v220
	global_load_lds_dwordx4 v164, s[20:21]
	s_add_i32 m0, s13, 0x400
	v_add_u32_e32 v165, s93, v232
	v_med3_i32 v165, v165, 0, s40
	v_lshl_or_b32 v165, v165, 7, v221
	global_load_lds_dwordx4 v165, s[20:21]
	s_waitcnt vmcnt(8)
	v_add_u32_e32 v154, s14, v223
	v_add_u32_e32 v155, s14, v224
	ds_read_b128 v[202:205], v154
	ds_read_b128 v[206:209], v155
	v_mfma_f32_16x16x32_bf16 v[4:7], v[88:91], v[72:75], 0
	v_mfma_f32_16x16x32_bf16 v[4:7], v[92:95], v[76:79], v[4:7]
	s_waitcnt lgkmcnt(0)
	s_add_i32 s93, s76, 0x300
	s_mov_b32 m0, s14
	v_add_u32_e32 v164, s93, v231
	v_med3_i32 v164, v164, 0, s40
	v_lshl_or_b32 v164, v164, 7, v220
	global_load_lds_dwordx4 v164, s[20:21]
	s_add_i32 m0, s14, 0x400
	v_add_u32_e32 v165, s93, v232
	v_med3_i32 v165, v165, 0, s40
	v_lshl_or_b32 v165, v165, 7, v221
	global_load_lds_dwordx4 v165, s[20:21]
	s_waitcnt vmcnt(8)
	v_add_u32_e32 v154, s15, v223
	v_add_u32_e32 v155, s15, v224
	ds_read_b128 v[88:91], v154
	ds_read_b128 v[92:95], v155
	v_mfma_f32_16x16x32_bf16 v[8:11], v[202:205], v[72:75], 0
	v_mfma_f32_16x16x32_bf16 v[8:11], v[206:209], v[76:79], v[8:11]
	s_waitcnt lgkmcnt(0)
	s_add_i32 s93, s76, 0x400
	s_mov_b32 m0, s15
	v_add_u32_e32 v164, s93, v231
	v_med3_i32 v164, v164, 0, s40
	v_lshl_or_b32 v164, v164, 7, v220
	global_load_lds_dwordx4 v164, s[20:21]
	s_add_i32 m0, s15, 0x400
	v_add_u32_e32 v165, s93, v232
	v_med3_i32 v165, v165, 0, s40
	v_lshl_or_b32 v165, v165, 7, v221
	global_load_lds_dwordx4 v165, s[20:21]
	s_waitcnt vmcnt(8)
	v_add_u32_e32 v154, s16, v223
	v_add_u32_e32 v155, s16, v224
	ds_read_b128 v[202:205], v154
	ds_read_b128 v[206:209], v155
	v_mfma_f32_16x16x32_bf16 v[12:15], v[88:91], v[72:75], 0
	v_mfma_f32_16x16x32_bf16 v[12:15], v[92:95], v[76:79], v[12:15]
	s_waitcnt lgkmcnt(0)
	s_add_i32 s93, s8, 0
	s_mov_b32 m0, s16
	v_add_u32_e32 v164, s93, v231
	v_lshl_or_b32 v164, v164, 7, v220
	global_load_lds_dwordx4 v164, s[18:19]
	s_add_i32 m0, s16, 0x400
	v_add_u32_e32 v165, s93, v232
	v_lshl_or_b32 v165, v165, 7, v221
	global_load_lds_dwordx4 v165, s[18:19]
	s_waitcnt vmcnt(8)
	v_add_u32_e32 v154, s12, v223
	v_add_u32_e32 v155, s12, v224
	ds_read_b128 v[88:91], v154
	ds_read_b128 v[92:95], v155
	v_mfma_f32_16x16x32_bf16 v[16:19], v[202:205], v[72:75], 0
	v_mfma_f32_16x16x32_bf16 v[16:19], v[206:209], v[76:79], v[16:19]
	s_waitcnt lgkmcnt(0)
	s_add_i32 s93, s8, 0xfffffc00
	s_mov_b32 m0, s12
	v_add_u32_e32 v164, s93, v231
	v_med3_i32 v164, v164, 0, s40
	v_lshl_or_b32 v164, v164, 7, v220
	global_load_lds_dwordx4 v164, s[20:21]
	s_add_i32 m0, s12, 0x400
	v_add_u32_e32 v165, s93, v232
	v_med3_i32 v165, v165, 0, s40
	v_lshl_or_b32 v165, v165, 7, v221
	global_load_lds_dwordx4 v165, s[20:21]
	s_waitcnt vmcnt(8)
	v_add_u32_e32 v154, s13, v223
	v_add_u32_e32 v155, s13, v224
	ds_read_b128 v[202:205], v154
	ds_read_b128 v[206:209], v155
	v_mfma_f32_16x16x32_bf16 v[20:23], v[88:91], v[72:75], 0
	v_mfma_f32_16x16x32_bf16 v[20:23], v[92:95], v[76:79], v[20:23]
	s_waitcnt lgkmcnt(0)
	s_add_i32 s93, s8, 0xfffffd00
	s_mov_b32 m0, s13
	v_add_u32_e32 v164, s93, v231
	v_med3_i32 v164, v164, 0, s40
	v_lshl_or_b32 v164, v164, 7, v220
	global_load_lds_dwordx4 v164, s[20:21]
	s_add_i32 m0, s13, 0x400
	v_add_u32_e32 v165, s93, v232
	v_med3_i32 v165, v165, 0, s40
	v_lshl_or_b32 v165, v165, 7, v221
	global_load_lds_dwordx4 v165, s[20:21]
	s_waitcnt vmcnt(8)
	v_add_u32_e32 v154, s14, v223
	v_add_u32_e32 v155, s14, v224
	ds_read_b128 v[88:91], v154
	ds_read_b128 v[92:95], v155
	v_mfma_f32_16x16x32_bf16 v[24:27], v[202:205], v[72:75], 0
	v_mfma_f32_16x16x32_bf16 v[24:27], v[206:209], v[76:79], v[24:27]
	s_waitcnt lgkmcnt(0)
	s_add_i32 s93, s8, 0xfffffe00
	s_mov_b32 m0, s14
	v_add_u32_e32 v164, s93, v231
	v_med3_i32 v164, v164, 0, s40
	v_lshl_or_b32 v164, v164, 7, v220
	global_load_lds_dwordx4 v164, s[20:21]
	s_add_i32 m0, s14, 0x400
	v_add_u32_e32 v165, s93, v232
	v_med3_i32 v165, v165, 0, s40
	v_lshl_or_b32 v165, v165, 7, v221
	global_load_lds_dwordx4 v165, s[20:21]
	s_waitcnt vmcnt(8)
	v_add_u32_e32 v154, s15, v223
	v_add_u32_e32 v155, s15, v224
	ds_read_b128 v[202:205], v154
	ds_read_b128 v[206:209], v155
	v_mfma_f32_16x16x32_bf16 v[28:31], v[88:91], v[72:75], 0
	v_mfma_f32_16x16x32_bf16 v[28:31], v[92:95], v[76:79], v[28:31]
	s_waitcnt lgkmcnt(0)
	s_add_i32 s93, s8, 0xffffff00
	s_mov_b32 m0, s15
	v_add_u32_e32 v164, s93, v231
	v_med3_i32 v164, v164, 0, s40
	v_lshl_or_b32 v164, v164, 7, v220
	global_load_lds_dwordx4 v164, s[20:21]
	s_add_i32 m0, s15, 0x400
	v_add_u32_e32 v165, s93, v232
	v_med3_i32 v165, v165, 0, s40
	v_lshl_or_b32 v165, v165, 7, v221
	global_load_lds_dwordx4 v165, s[20:21]
	s_waitcnt vmcnt(8)
	v_add_u32_e32 v154, s16, v223
	v_add_u32_e32 v155, s16, v224
	ds_read_b128 v[80:83], v154
	ds_read_b128 v[84:87], v155
	v_mfma_f32_16x16x32_bf16 v[32:35], v[202:205], v[72:75], 0
	v_mfma_f32_16x16x32_bf16 v[32:35], v[206:209], v[76:79], v[32:35]
	s_waitcnt lgkmcnt(0)
	s_add_i32 s93, s8, 0
	s_mov_b32 m0, s16
	v_add_u32_e32 v164, s93, v231
	v_med3_i32 v164, v164, 0, s40
	v_lshl_or_b32 v164, v164, 7, v220
	global_load_lds_dwordx4 v164, s[20:21]
	s_add_i32 m0, s16, 0x400
	v_add_u32_e32 v165, s93, v232
	v_med3_i32 v165, v165, 0, s40
	v_lshl_or_b32 v165, v165, 7, v221
	global_load_lds_dwordx4 v165, s[20:21]
	s_waitcnt vmcnt(8)
	v_add_u32_e32 v154, s12, v223
	v_add_u32_e32 v155, s12, v224
	ds_read_b128 v[202:205], v154
	ds_read_b128 v[206:209], v155
	v_mov_b32_e32 v188, s84
	v_lshl_add_u32 v188, v216, 4, v188
	v_lshrrev_b32_e32 v146, 4, v188
	v_xor_b32_e32 v146, v146, v188
	v_and_b32_e32 v146, 15, v146
	v_lshlrev_b32_e32 v147, 8, v188
	v_or_b32_e32 v148, 0, v217
	v_xor_b32_e32 v148, v148, v146
	v_lshl_add_u32 v190, v148, 4, v147
	v_or_b32_e32 v148, 4, v217
	v_xor_b32_e32 v148, v148, v146
	v_lshl_add_u32 v191, v148, 4, v147
	v_or_b32_e32 v148, 8, v217
	v_xor_b32_e32 v148, v148, v146
	v_lshl_add_u32 v192, v148, 4, v147
	v_or_b32_e32 v148, 12, v217
	v_xor_b32_e32 v148, v148, v146
	v_lshl_add_u32 v193, v148, 4, v147
	v_lshlrev_b32_e32 v194, 3, v188
	v_add_u32_e32 v194, 0x10000, v194
	ds_read_b64 v[144:145], v194
	ds_read_b128 v[128:131], v190
	ds_read_b128 v[132:135], v191
	ds_read_b128 v[136:139], v192
	ds_read_b128 v[140:143], v193
	s_ashr_i32 s77, s76, 4
	s_sub_i32 s77, 64, s77
	s_sub_i32 s78, s40, s76
	s_waitcnt lgkmcnt(0)
	s_add_i32 s93, s8, 0x100
	s_mov_b32 m0, s12
	v_add_u32_e32 v164, s93, v231
	v_med3_i32 v164, v164, 0, s40
	v_lshl_or_b32 v164, v164, 7, v220
	global_load_lds_dwordx4 v164, s[20:21]
	s_add_i32 m0, s12, 0x400
	v_add_u32_e32 v165, s93, v232
	v_med3_i32 v165, v165, 0, s40
	v_lshl_or_b32 v165, v165, 7, v221
	global_load_lds_dwordx4 v165, s[20:21]
	s_waitcnt vmcnt(8)
	v_add_u32_e32 v154, s13, v223
	v_add_u32_e32 v155, s13, v224
	ds_read_b128 v[88:91], v154
	ds_read_b128 v[92:95], v155
	v_mfma_f32_16x16x32_bf16 v[36:39], v[202:205], v[80:83], 0
	v_mfma_f32_16x16x32_bf16 v[36:39], v[206:209], v[84:87], v[36:39]
	s_ashr_i32 s78, s78, 4
	s_add_i32 s78, s78, 64
	v_cndmask_b32_e64 v0, v0, v230, s[52:53]
	v_cndmask_b32_e64 v32, v32, v230, s[62:63]
	v_cndmask_b32_e64 v1, v1, v230, s[56:57]
	v_cndmask_b32_e64 v33, v33, v230, s[64:65]
	v_cndmask_b32_e64 v2, v2, v230, s[58:59]
	v_cndmask_b32_e64 v34, v34, v230, s[70:71]
	v_cndmask_b32_e64 v3, v3, v230, s[60:61]
	v_cndmask_b32_e64 v35, v35, v230, s[72:73]
	v_sub_u32_e32 v200, s77, v229
	s_sub_i32 s91, s78, s77
	v_sub_u32_e32 v150, 0, v200
	v_sub_u32_e32 v151, 1, v200
	v_sub_u32_e32 v152, 2, v200
	v_sub_u32_e32 v153, 3, v200
	v_cmp_lt_u32_e64 s[94:95], s91, v150
	v_cmp_lt_u32_e64 s[86:87], s91, v151
	v_cmp_lt_u32_e64 s[0:1], s91, v152
	v_cmp_lt_u32_e64 s[2:3], s91, v153
	v_cndmask_b32_e64 v0, v0, v230, s[94:95]
	v_cndmask_b32_e64 v1, v1, v230, s[86:87]
	v_cndmask_b32_e64 v2, v2, v230, s[0:1]
	v_cndmask_b32_e64 v3, v3, v230, s[2:3]
	v_sub_u32_e32 v150, 16, v200
	v_sub_u32_e32 v151, 17, v200
	v_sub_u32_e32 v152, 18, v200
	v_sub_u32_e32 v153, 19, v200
	s_waitcnt lgkmcnt(0)
	s_add_i32 s93, s8, 0x200
	s_mov_b32 m0, s13
	v_add_u32_e32 v164, s93, v231
	v_med3_i32 v164, v164, 0, s40
	v_lshl_or_b32 v164, v164, 7, v220
	global_load_lds_dwordx4 v164, s[20:21]
	s_add_i32 m0, s13, 0x400
	v_add_u32_e32 v165, s93, v232
	v_med3_i32 v165, v165, 0, s40
	v_lshl_or_b32 v165, v165, 7, v221
	global_load_lds_dwordx4 v165, s[20:21]
	s_waitcnt vmcnt(8)
	v_add_u32_e32 v154, s14, v223
	v_add_u32_e32 v155, s14, v224
	ds_read_b128 v[202:205], v154
	ds_read_b128 v[206:209], v155
	v_mfma_f32_16x16x32_bf16 v[40:43], v[88:91], v[80:83], 0
	v_mfma_f32_16x16x32_bf16 v[40:43], v[92:95], v[84:87], v[40:43]
	v_cmp_lt_u32_e64 s[94:95], s91, v150
	v_cmp_lt_u32_e64 s[86:87], s91, v151
	v_cmp_lt_u32_e64 s[0:1], s91, v152
	v_cmp_lt_u32_e64 s[2:3], s91, v153
	v_cndmask_b32_e64 v4, v4, v230, s[94:95]
	v_cndmask_b32_e64 v5, v5, v230, s[86:87]
	v_cndmask_b32_e64 v6, v6, v230, s[0:1]
	v_cndmask_b32_e64 v7, v7, v230, s[2:3]
	v_sub_u32_e32 v150, 32, v200
	v_sub_u32_e32 v151, 33, v200
	v_sub_u32_e32 v152, 34, v200
	v_sub_u32_e32 v153, 35, v200
	v_cmp_lt_u32_e64 s[94:95], s91, v150
	v_cmp_lt_u32_e64 s[86:87], s91, v151
	v_cmp_lt_u32_e64 s[0:1], s91, v152
	v_cmp_lt_u32_e64 s[2:3], s91, v153
	v_cndmask_b32_e64 v8, v8, v230, s[94:95]
	v_cndmask_b32_e64 v9, v9, v230, s[86:87]
	v_cndmask_b32_e64 v10, v10, v230, s[0:1]
	v_cndmask_b32_e64 v11, v11, v230, s[2:3]
	v_sub_u32_e32 v150, 48, v200
	v_sub_u32_e32 v151, 49, v200
	v_sub_u32_e32 v152, 50, v200
	v_sub_u32_e32 v153, 51, v200
	v_cmp_lt_u32_e64 s[94:95], s91, v150
	v_cmp_lt_u32_e64 s[86:87], s91, v151
	v_cmp_lt_u32_e64 s[0:1], s91, v152
	v_cmp_lt_u32_e64 s[2:3], s91, v153
	s_waitcnt lgkmcnt(0)
	s_add_i32 s93, s8, 0x300
	s_mov_b32 m0, s14
	v_add_u32_e32 v164, s93, v231
	v_med3_i32 v164, v164, 0, s40
	v_lshl_or_b32 v164, v164, 7, v220
	global_load_lds_dwordx4 v164, s[20:21]
	s_add_i32 m0, s14, 0x400
	v_add_u32_e32 v165, s93, v232
	v_med3_i32 v165, v165, 0, s40
	v_lshl_or_b32 v165, v165, 7, v221
	global_load_lds_dwordx4 v165, s[20:21]
	s_waitcnt vmcnt(8)
	v_add_u32_e32 v154, s15, v223
	v_add_u32_e32 v155, s15, v224
	ds_read_b128 v[88:91], v154
	ds_read_b128 v[92:95], v155
	v_mfma_f32_16x16x32_bf16 v[44:47], v[202:205], v[80:83], 0
	v_mfma_f32_16x16x32_bf16 v[44:47], v[206:209], v[84:87], v[44:47]
	v_cndmask_b32_e64 v12, v12, v230, s[94:95]
	v_cndmask_b32_e64 v13, v13, v230, s[86:87]
	v_cndmask_b32_e64 v14, v14, v230, s[0:1]
	v_cndmask_b32_e64 v15, v15, v230, s[2:3]
	v_sub_u32_e32 v150, 64, v200
	v_sub_u32_e32 v151, 0x41, v200
	v_sub_u32_e32 v152, 0x42, v200
	v_sub_u32_e32 v153, 0x43, v200
	v_cmp_lt_u32_e64 s[94:95], s91, v150
	v_cmp_lt_u32_e64 s[86:87], s91, v151
	v_cmp_lt_u32_e64 s[0:1], s91, v152
	v_cmp_lt_u32_e64 s[2:3], s91, v153
	v_cndmask_b32_e64 v16, v16, v230, s[94:95]
	v_cndmask_b32_e64 v17, v17, v230, s[86:87]
	v_cndmask_b32_e64 v18, v18, v230, s[0:1]
	v_cndmask_b32_e64 v19, v19, v230, s[2:3]
	v_sub_u32_e32 v150, 0x50, v200
	v_sub_u32_e32 v151, 0x51, v200
	v_sub_u32_e32 v152, 0x52, v200
	v_sub_u32_e32 v153, 0x53, v200
	v_cmp_lt_u32_e64 s[94:95], s91, v150
	v_cmp_lt_u32_e64 s[86:87], s91, v151
	v_cmp_lt_u32_e64 s[0:1], s91, v152
	v_cmp_lt_u32_e64 s[2:3], s91, v153
	v_cndmask_b32_e64 v20, v20, v230, s[94:95]
	v_cndmask_b32_e64 v21, v21, v230, s[86:87]
	v_cndmask_b32_e64 v22, v22, v230, s[0:1]
	v_cndmask_b32_e64 v23, v23, v230, s[2:3]
	s_waitcnt lgkmcnt(0)
	s_add_i32 s93, s8, 0x400
	s_mov_b32 m0, s15
	v_add_u32_e32 v164, s93, v231
	v_med3_i32 v164, v164, 0, s40
	v_lshl_or_b32 v164, v164, 7, v220
	global_load_lds_dwordx4 v164, s[20:21]
	s_add_i32 m0, s15, 0x400
	v_add_u32_e32 v165, s93, v232
	v_med3_i32 v165, v165, 0, s40
	v_lshl_or_b32 v165, v165, 7, v221
	global_load_lds_dwordx4 v165, s[20:21]
	s_waitcnt vmcnt(8)
	v_add_u32_e32 v154, s16, v223
	v_add_u32_e32 v155, s16, v224
	ds_read_b128 v[202:205], v154
	ds_read_b128 v[206:209], v155
	v_mfma_f32_16x16x32_bf16 v[48:51], v[88:91], v[80:83], 0
	v_mfma_f32_16x16x32_bf16 v[48:51], v[92:95], v[84:87], v[48:51]
	v_sub_u32_e32 v150, 0x60, v200
	v_sub_u32_e32 v151, 0x61, v200
	v_sub_u32_e32 v152, 0x62, v200
	v_sub_u32_e32 v153, 0x63, v200
	v_cmp_lt_u32_e64 s[94:95], s91, v150
	v_cmp_lt_u32_e64 s[86:87], s91, v151
	v_cmp_lt_u32_e64 s[0:1], s91, v152
	v_cmp_lt_u32_e64 s[2:3], s91, v153
	v_cndmask_b32_e64 v24, v24, v230, s[94:95]
	v_cndmask_b32_e64 v25, v25, v230, s[86:87]
	v_cndmask_b32_e64 v26, v26, v230, s[0:1]
	v_cndmask_b32_e64 v27, v27, v230, s[2:3]
	v_sub_u32_e32 v150, 0x70, v200
	v_sub_u32_e32 v151, 0x71, v200
	v_sub_u32_e32 v152, 0x72, v200
	v_sub_u32_e32 v153, 0x73, v200
	v_cmp_lt_u32_e64 s[94:95], s91, v150
	v_cmp_lt_u32_e64 s[86:87], s91, v151
	v_cmp_lt_u32_e64 s[0:1], s91, v152
	v_cmp_lt_u32_e64 s[2:3], s91, v153
	v_cndmask_b32_e64 v28, v28, v230, s[94:95]
	v_cndmask_b32_e64 v29, v29, v230, s[86:87]
	v_cndmask_b32_e64 v30, v30, v230, s[0:1]
	v_cndmask_b32_e64 v31, v31, v230, s[2:3]
	v_sub_u32_e32 v150, 0x80, v200
	v_sub_u32_e32 v151, 0x81, v200
	v_sub_u32_e32 v152, 0x82, v200
	v_sub_u32_e32 v153, 0x83, v200
	s_waitcnt lgkmcnt(0)
	s_add_i32 s93, s76, 0xfffffc00
	s_mov_b32 m0, s16
	v_add_u32_e32 v164, s93, v231
	v_med3_i32 v164, v164, 0, s40
	v_lshl_or_b32 v164, v164, 7, v222
	global_load_lds_dwordx4 v164, s[24:25]
	s_add_i32 m0, s16, 0x400
	v_add_u32_e32 v165, s93, v232
	v_med3_i32 v165, v165, 0, s40
	v_lshl_or_b32 v165, v165, 7, v222
	global_load_lds_dwordx4 v165, s[24:25]
	s_waitcnt vmcnt(8)
	v_add_u32_e32 v154, s12, v223
	v_add_u32_e32 v155, s12, v224
	ds_read_b128 v[88:91], v154
	ds_read_b128 v[92:95], v155
	v_mfma_f32_16x16x32_bf16 v[52:55], v[202:205], v[80:83], 0
	v_mfma_f32_16x16x32_bf16 v[52:55], v[206:209], v[84:87], v[52:55]
	v_cmp_lt_u32_e64 s[94:95], s91, v150
	v_cmp_lt_u32_e64 s[86:87], s91, v151
	v_cmp_lt_u32_e64 s[0:1], s91, v152
	v_cmp_lt_u32_e64 s[2:3], s91, v153
	v_cndmask_b32_e64 v32, v32, v230, s[94:95]
	v_cndmask_b32_e64 v33, v33, v230, s[86:87]
	v_cndmask_b32_e64 v34, v34, v230, s[0:1]
	v_cndmask_b32_e64 v35, v35, v230, s[2:3]
	v_max3_f32 v184, v0, v1, v2
	v_max3_f32 v184, v184, v3, v4
	v_max3_f32 v184, v184, v5, v6
	v_max3_f32 v184, v184, v7, v8
	v_max3_f32 v184, v184, v9, v10
	v_max3_f32 v184, v184, v11, v12
	v_max3_f32 v184, v184, v13, v14
	v_max3_f32 v184, v184, v15, v16
	v_max3_f32 v184, v184, v17, v18
	v_max3_f32 v184, v184, v19, v20
	v_max3_f32 v184, v184, v21, v22
	v_max3_f32 v184, v184, v23, v24
	v_max3_f32 v184, v184, v25, v26
	v_max3_f32 v184, v184, v27, v28
	v_max3_f32 v184, v184, v29, v30
	v_max3_f32 v184, v184, v31, v32
	v_max3_f32 v184, v184, v33, v34
	v_max_f32_e32 v184, v184, v35
	v_mov_b32_e32 v146, v184
	s_nop 1
	v_permlane16_swap_b32_e32 v184, v146
	s_waitcnt lgkmcnt(0)
	s_add_i32 s93, s76, 0xfffffd00
	s_mov_b32 m0, s12
	v_add_u32_e32 v164, s93, v231
	v_med3_i32 v164, v164, 0, s40
	v_lshl_or_b32 v164, v164, 7, v222
	global_load_lds_dwordx4 v164, s[24:25]
	s_add_i32 m0, s12, 0x400
	v_add_u32_e32 v165, s93, v232
	v_med3_i32 v165, v165, 0, s40
	v_lshl_or_b32 v165, v165, 7, v222
	global_load_lds_dwordx4 v165, s[24:25]
	s_waitcnt vmcnt(8)
	v_add_u32_e32 v154, s13, v223
	v_add_u32_e32 v155, s13, v224
	ds_read_b128 v[202:205], v154
	ds_read_b128 v[206:209], v155
	v_mfma_f32_16x16x32_bf16 v[56:59], v[88:91], v[80:83], 0
	v_mfma_f32_16x16x32_bf16 v[56:59], v[92:95], v[84:87], v[56:59]
	v_max_f32_e32 v184, v184, v146
	v_mov_b32_e32 v146, v184
	s_nop 1
	v_permlane32_swap_b32_e32 v184, v146
	v_max_f32_e32 v184, v184, v146
	v_pk_add_f32 v[0:1], v[0:1], v[184:185] op_sel_hi:[1,0] neg_lo:[0,1] neg_hi:[0,1]
	v_pk_add_f32 v[2:3], v[2:3], v[184:185] op_sel_hi:[1,0] neg_lo:[0,1] neg_hi:[0,1]
	v_pk_add_f32 v[4:5], v[4:5], v[184:185] op_sel_hi:[1,0] neg_lo:[0,1] neg_hi:[0,1]
	v_pk_add_f32 v[6:7], v[6:7], v[184:185] op_sel_hi:[1,0] neg_lo:[0,1] neg_hi:[0,1]
	v_exp_f32_e32 v0, v0
	v_exp_f32_e32 v1, v1
	v_exp_f32_e32 v2, v2
	v_exp_f32_e32 v3, v3
	v_pk_add_f32 v[8:9], v[8:9], v[184:185] op_sel_hi:[1,0] neg_lo:[0,1] neg_hi:[0,1]
	v_pk_add_f32 v[10:11], v[10:11], v[184:185] op_sel_hi:[1,0] neg_lo:[0,1] neg_hi:[0,1]
	v_exp_f32_e32 v4, v4
	v_exp_f32_e32 v5, v5
	v_exp_f32_e32 v6, v6
	v_exp_f32_e32 v7, v7
	v_pk_add_f32 v[12:13], v[12:13], v[184:185] op_sel_hi:[1,0] neg_lo:[0,1] neg_hi:[0,1]
	v_pk_add_f32 v[14:15], v[14:15], v[184:185] op_sel_hi:[1,0] neg_lo:[0,1] neg_hi:[0,1]
	v_exp_f32_e32 v8, v8
	v_exp_f32_e32 v9, v9
	v_exp_f32_e32 v10, v10
	v_exp_f32_e32 v11, v11
	v_pk_add_f32 v[16:17], v[16:17], v[184:185] op_sel_hi:[1,0] neg_lo:[0,1] neg_hi:[0,1]
	v_pk_add_f32 v[18:19], v[18:19], v[184:185] op_sel_hi:[1,0] neg_lo:[0,1] neg_hi:[0,1]
	v_exp_f32_e32 v12, v12
	v_exp_f32_e32 v13, v13
	s_waitcnt lgkmcnt(0)
	s_add_i32 s93, s76, 0xfffffe00
	s_mov_b32 m0, s13
	v_add_u32_e32 v164, s93, v231
	v_med3_i32 v164, v164, 0, s40
	v_lshl_or_b32 v164, v164, 7, v222
	global_load_lds_dwordx4 v164, s[24:25]
	s_add_i32 m0, s13, 0x400
	v_add_u32_e32 v165, s93, v232
	v_med3_i32 v165, v165, 0, s40
	v_lshl_or_b32 v165, v165, 7, v222
	global_load_lds_dwordx4 v165, s[24:25]
	s_waitcnt vmcnt(8)
	v_add_u32_e32 v154, s14, v223
	v_add_u32_e32 v155, s14, v224
	ds_read_b128 v[88:91], v154
	ds_read_b128 v[92:95], v155
	v_mfma_f32_16x16x32_bf16 v[60:63], v[202:205], v[80:83], 0
	v_mfma_f32_16x16x32_bf16 v[60:63], v[206:209], v[84:87], v[60:63]
	v_exp_f32_e32 v14, v14
	v_exp_f32_e32 v15, v15
	v_pk_add_f32 v[20:21], v[20:21], v[184:185] op_sel_hi:[1,0] neg_lo:[0,1] neg_hi:[0,1]
	v_pk_add_f32 v[22:23], v[22:23], v[184:185] op_sel_hi:[1,0] neg_lo:[0,1] neg_hi:[0,1]
	v_exp_f32_e32 v16, v16
	v_exp_f32_e32 v17, v17
	v_exp_f32_e32 v18, v18
	v_exp_f32_e32 v19, v19
	v_pk_add_f32 v[24:25], v[24:25], v[184:185] op_sel_hi:[1,0] neg_lo:[0,1] neg_hi:[0,1]
	v_pk_add_f32 v[26:27], v[26:27], v[184:185] op_sel_hi:[1,0] neg_lo:[0,1] neg_hi:[0,1]
	v_exp_f32_e32 v20, v20
	v_exp_f32_e32 v21, v21
	v_exp_f32_e32 v22, v22
	v_exp_f32_e32 v23, v23
	v_pk_add_f32 v[28:29], v[28:29], v[184:185] op_sel_hi:[1,0] neg_lo:[0,1] neg_hi:[0,1]
	v_pk_add_f32 v[30:31], v[30:31], v[184:185] op_sel_hi:[1,0] neg_lo:[0,1] neg_hi:[0,1]
	v_exp_f32_e32 v24, v24
	v_exp_f32_e32 v25, v25
	v_exp_f32_e32 v26, v26
	v_exp_f32_e32 v27, v27
	v_pk_add_f32 v[32:33], v[32:33], v[184:185] op_sel_hi:[1,0] neg_lo:[0,1] neg_hi:[0,1]
	v_pk_add_f32 v[34:35], v[34:35], v[184:185] op_sel_hi:[1,0] neg_lo:[0,1] neg_hi:[0,1]
	v_exp_f32_e32 v28, v28
	v_exp_f32_e32 v29, v29
	v_exp_f32_e32 v30, v30
	v_exp_f32_e32 v31, v31
	v_exp_f32_e32 v32, v32
	v_exp_f32_e32 v33, v33
	s_waitcnt lgkmcnt(0)
	s_add_i32 s93, s76, 0xffffff00
	s_mov_b32 m0, s14
	v_add_u32_e32 v164, s93, v231
	v_med3_i32 v164, v164, 0, s40
	v_lshl_or_b32 v164, v164, 7, v222
	global_load_lds_dwordx4 v164, s[24:25]
	s_add_i32 m0, s14, 0x400
	v_add_u32_e32 v165, s93, v232
	v_med3_i32 v165, v165, 0, s40
	v_lshl_or_b32 v165, v165, 7, v222
	global_load_lds_dwordx4 v165, s[24:25]
	s_waitcnt vmcnt(8)
	v_add_u32_e32 v154, s15, v223
	v_add_u32_e32 v155, s15, v224
	ds_read_b128 v[202:205], v154
	ds_read_b128 v[206:209], v155
	v_mfma_f32_16x16x32_bf16 v[64:67], v[88:91], v[80:83], 0
	v_mfma_f32_16x16x32_bf16 v[64:67], v[92:95], v[84:87], v[64:67]
	v_exp_f32_e32 v34, v34
	v_exp_f32_e32 v35, v35
	s_nop 0
	v_pk_add_f32 v[146:147], v[0:1], v[2:3]
	v_pk_add_f32 v[148:149], v[4:5], v[6:7]
	v_pk_add_f32 v[146:147], v[146:147], v[8:9]
	v_pk_add_f32 v[148:149], v[148:149], v[10:11]
	v_pk_add_f32 v[146:147], v[146:147], v[12:13]
	v_pk_add_f32 v[148:149], v[148:149], v[14:15]
	v_pk_add_f32 v[146:147], v[146:147], v[16:17]
	v_pk_add_f32 v[148:149], v[148:149], v[18:19]
	v_pk_add_f32 v[146:147], v[146:147], v[20:21]
	v_pk_add_f32 v[148:149], v[148:149], v[22:23]
	v_pk_add_f32 v[146:147], v[146:147], v[24:25]
	v_pk_add_f32 v[148:149], v[148:149], v[26:27]
	v_pk_add_f32 v[146:147], v[146:147], v[28:29]
	v_pk_add_f32 v[148:149], v[148:149], v[30:31]
	v_pk_add_f32 v[146:147], v[146:147], v[32:33]
	v_pk_add_f32 v[148:149], v[148:149], v[34:35]
	s_nop 0
	v_pk_add_f32 v[146:147], v[146:147], v[148:149]
	s_nop 0
	v_add_f32_e32 v185, v146, v147
	v_cvt_pk_bf16_f32 v0, v0, v1
	v_cvt_pk_bf16_f32 v1, v2, v3
	v_cvt_pk_bf16_f32 v4, v4, v5
	v_cvt_pk_bf16_f32 v5, v6, v7
	v_cvt_pk_bf16_f32 v8, v8, v9
	s_waitcnt lgkmcnt(0)
	s_add_i32 s93, s76, 0
	s_mov_b32 m0, s15
	v_add_u32_e32 v164, s93, v231
	v_med3_i32 v164, v164, 0, s40
	v_lshl_or_b32 v164, v164, 7, v222
	global_load_lds_dwordx4 v164, s[24:25]
	s_add_i32 m0, s15, 0x400
	v_add_u32_e32 v165, s93, v232
	v_med3_i32 v165, v165, 0, s40
	v_lshl_or_b32 v165, v165, 7, v222
	global_load_lds_dwordx4 v165, s[24:25]
	s_waitcnt vmcnt(8)
	v_add_u32_e32 v154, s16, v225
	v_add_u32_e32 v155, s16, v226
	v_add_u32_e32 v156, s16, v227
	v_add_u32_e32 v157, s16, v228
	ds_read_b64_tr_b16 v[88:89], v154
	ds_read_b64_tr_b16 v[90:91], v155
	ds_read_b64_tr_b16 v[92:93], v156
	ds_read_b64_tr_b16 v[94:95], v157
	v_mfma_f32_16x16x32_bf16 v[68:71], v[202:205], v[80:83], 0
	v_mfma_f32_16x16x32_bf16 v[68:71], v[206:209], v[84:87], v[68:71]
	v_cvt_pk_bf16_f32 v9, v10, v11
	v_cvt_pk_bf16_f32 v12, v12, v13
	v_cvt_pk_bf16_f32 v13, v14, v15
	v_cvt_pk_bf16_f32 v16, v16, v17
	v_cvt_pk_bf16_f32 v17, v18, v19
	v_cvt_pk_bf16_f32 v20, v20, v21
	v_cvt_pk_bf16_f32 v21, v22, v23
	v_cvt_pk_bf16_f32 v24, v24, v25
	v_cvt_pk_bf16_f32 v25, v26, v27
	v_cvt_pk_bf16_f32 v28, v28, v29
	v_cvt_pk_bf16_f32 v29, v30, v31
	v_cvt_pk_bf16_f32 v32, v32, v33
	v_cvt_pk_bf16_f32 v33, v34, v35
	v_mov_b32_e32 v146, v185
	s_nop 1
	v_permlane16_swap_b32_e32 v185, v146
	v_add_f32_e32 v185, v185, v146
	v_mov_b32_e32 v146, v185
	s_nop 1
	v_permlane32_swap_b32_e32 v185, v146
	v_add_f32_e32 v185, v185, v146
	s_waitcnt lgkmcnt(0)
	s_add_i32 s93, s76, 0x100
	s_mov_b32 m0, s16
	v_add_u32_e32 v164, s93, v231
	v_med3_i32 v164, v164, 0, s40
	v_lshl_or_b32 v164, v164, 7, v222
	global_load_lds_dwordx4 v164, s[24:25]
	s_add_i32 m0, s16, 0x400
	v_add_u32_e32 v165, s93, v232
	v_med3_i32 v165, v165, 0, s40
	v_lshl_or_b32 v165, v165, 7, v222
	global_load_lds_dwordx4 v165, s[24:25]
	s_waitcnt vmcnt(8)
	v_add_u32_e32 v154, s12, v225
	v_add_u32_e32 v155, s12, v226
	v_add_u32_e32 v156, s12, v227
	v_add_u32_e32 v157, s12, v228
	ds_read_b64_tr_b16 v[202:203], v154
	ds_read_b64_tr_b16 v[204:205], v155
	ds_read_b64_tr_b16 v[206:207], v156
	ds_read_b64_tr_b16 v[208:209], v157
	v_mfma_f32_16x16x16_bf16 v[96:99], v[88:89], v[0:1], 0
	v_mfma_f32_16x16x16_bf16 v[100:103], v[90:91], v[0:1], 0
	v_mfma_f32_16x16x16_bf16 v[104:107], v[92:93], v[0:1], 0
	v_mfma_f32_16x16x16_bf16 v[108:111], v[94:95], v[0:1], 0
	v_mov_b32_e32 v189, s85
	v_lshl_add_u32 v189, v216, 4, v189
	v_lshrrev_b32_e32 v146, 4, v189
	v_xor_b32_e32 v146, v146, v189
	v_and_b32_e32 v146, 15, v146
	v_lshlrev_b32_e32 v147, 8, v189
	v_or_b32_e32 v148, 0, v217
	v_xor_b32_e32 v148, v148, v146
	v_lshl_add_u32 v195, v148, 4, v147
	v_or_b32_e32 v148, 4, v217
	v_xor_b32_e32 v148, v148, v146
	v_lshl_add_u32 v196, v148, 4, v147
	v_or_b32_e32 v148, 8, v217
	v_xor_b32_e32 v148, v148, v146
	v_lshl_add_u32 v197, v148, 4, v147
	v_or_b32_e32 v148, 12, v217
	v_xor_b32_e32 v148, v148, v146
	v_lshl_add_u32 v198, v148, 4, v147
	v_lshlrev_b32_e32 v199, 3, v189
	v_add_u32_e32 v199, 0x10000, v199
	ds_read_b64 v[182:183], v199
	ds_read_b128 v[166:169], v195
	ds_read_b128 v[170:173], v196
	ds_read_b128 v[174:177], v197
	ds_read_b128 v[178:181], v198
	s_ashr_i32 s77, s8, 4
	s_sub_i32 s77, 64, s77
	s_sub_i32 s78, s40, s8
	s_ashr_i32 s78, s78, 4
	s_add_i32 s78, s78, 64
	v_cndmask_b32_e64 v36, v36, v230, s[52:53]
	s_waitcnt lgkmcnt(0)
	s_add_i32 s93, s76, 0x200
	s_mov_b32 m0, s12
	v_add_u32_e32 v164, s93, v231
	v_med3_i32 v164, v164, 0, s40
	v_lshl_or_b32 v164, v164, 7, v222
	global_load_lds_dwordx4 v164, s[24:25]
	s_add_i32 m0, s12, 0x400
	v_add_u32_e32 v165, s93, v232
	v_med3_i32 v165, v165, 0, s40
	v_lshl_or_b32 v165, v165, 7, v222
	global_load_lds_dwordx4 v165, s[24:25]
	s_waitcnt vmcnt(8)
	v_add_u32_e32 v154, s13, v225
	v_add_u32_e32 v155, s13, v226
	v_add_u32_e32 v156, s13, v227
	v_add_u32_e32 v157, s13, v228
	ds_read_b64_tr_b16 v[88:89], v154
	ds_read_b64_tr_b16 v[90:91], v155
	ds_read_b64_tr_b16 v[92:93], v156
	ds_read_b64_tr_b16 v[94:95], v157
	v_mfma_f32_16x16x16_bf16 v[96:99], v[202:203], v[4:5], v[96:99]
	v_mfma_f32_16x16x16_bf16 v[100:103], v[204:205], v[4:5], v[100:103]
	v_mfma_f32_16x16x16_bf16 v[104:107], v[206:207], v[4:5], v[104:107]
	v_mfma_f32_16x16x16_bf16 v[108:111], v[208:209], v[4:5], v[108:111]
	v_cndmask_b32_e64 v68, v68, v230, s[62:63]
	v_cndmask_b32_e64 v37, v37, v230, s[56:57]
	v_cndmask_b32_e64 v69, v69, v230, s[64:65]
	v_cndmask_b32_e64 v38, v38, v230, s[58:59]
	v_cndmask_b32_e64 v70, v70, v230, s[70:71]
	v_cndmask_b32_e64 v39, v39, v230, s[60:61]
	v_cndmask_b32_e64 v71, v71, v230, s[72:73]
	v_sub_u32_e32 v200, s77, v229
	s_sub_i32 s91, s78, s77
	v_sub_u32_e32 v150, 0, v200
	v_sub_u32_e32 v151, 1, v200
	v_sub_u32_e32 v152, 2, v200
	v_sub_u32_e32 v153, 3, v200
	v_cmp_lt_u32_e64 s[94:95], s91, v150
	v_cmp_lt_u32_e64 s[86:87], s91, v151
	v_cmp_lt_u32_e64 s[0:1], s91, v152
	v_cmp_lt_u32_e64 s[2:3], s91, v153
	v_cndmask_b32_e64 v36, v36, v230, s[94:95]
	v_cndmask_b32_e64 v37, v37, v230, s[86:87]
	v_cndmask_b32_e64 v38, v38, v230, s[0:1]
	v_cndmask_b32_e64 v39, v39, v230, s[2:3]
	v_sub_u32_e32 v150, 16, v200
	v_sub_u32_e32 v151, 17, v200
	v_sub_u32_e32 v152, 18, v200
	v_sub_u32_e32 v153, 19, v200
	v_cmp_lt_u32_e64 s[94:95], s91, v150
	v_cmp_lt_u32_e64 s[86:87], s91, v151
	v_cmp_lt_u32_e64 s[0:1], s91, v152
	v_cmp_lt_u32_e64 s[2:3], s91, v153
	v_cndmask_b32_e64 v40, v40, v230, s[94:95]
	v_cndmask_b32_e64 v41, v41, v230, s[86:87]
	s_waitcnt lgkmcnt(0)
	s_add_i32 s93, s76, 0x300
	s_mov_b32 m0, s13
	v_add_u32_e32 v164, s93, v231
	v_med3_i32 v164, v164, 0, s40
	v_lshl_or_b32 v164, v164, 7, v222
	global_load_lds_dwordx4 v164, s[24:25]
	s_add_i32 m0, s13, 0x400
	v_add_u32_e32 v165, s93, v232
	v_med3_i32 v165, v165, 0, s40
	v_lshl_or_b32 v165, v165, 7, v222
	global_load_lds_dwordx4 v165, s[24:25]
	s_waitcnt vmcnt(8)
	v_add_u32_e32 v154, s14, v225
	v_add_u32_e32 v155, s14, v226
	v_add_u32_e32 v156, s14, v227
	v_add_u32_e32 v157, s14, v228
	ds_read_b64_tr_b16 v[202:203], v154
	ds_read_b64_tr_b16 v[204:205], v155
	ds_read_b64_tr_b16 v[206:207], v156
	ds_read_b64_tr_b16 v[208:209], v157
	v_mfma_f32_16x16x16_bf16 v[96:99], v[88:89], v[8:9], v[96:99]
	v_mfma_f32_16x16x16_bf16 v[100:103], v[90:91], v[8:9], v[100:103]
	v_mfma_f32_16x16x16_bf16 v[104:107], v[92:93], v[8:9], v[104:107]
	v_mfma_f32_16x16x16_bf16 v[108:111], v[94:95], v[8:9], v[108:111]
	v_cndmask_b32_e64 v42, v42, v230, s[0:1]
	v_cndmask_b32_e64 v43, v43, v230, s[2:3]
	v_sub_u32_e32 v150, 32, v200
	v_sub_u32_e32 v151, 33, v200
	v_sub_u32_e32 v152, 34, v200
	v_sub_u32_e32 v153, 35, v200
	v_cmp_lt_u32_e64 s[94:95], s91, v150
	v_cmp_lt_u32_e64 s[86:87], s91, v151
	v_cmp_lt_u32_e64 s[0:1], s91, v152
	v_cmp_lt_u32_e64 s[2:3], s91, v153
	v_cndmask_b32_e64 v44, v44, v230, s[94:95]
	v_cndmask_b32_e64 v45, v45, v230, s[86:87]
	v_cndmask_b32_e64 v46, v46, v230, s[0:1]
	v_cndmask_b32_e64 v47, v47, v230, s[2:3]
	v_sub_u32_e32 v150, 48, v200
	v_sub_u32_e32 v151, 49, v200
	v_sub_u32_e32 v152, 50, v200
	v_sub_u32_e32 v153, 51, v200
	v_cmp_lt_u32_e64 s[94:95], s91, v150
	v_cmp_lt_u32_e64 s[86:87], s91, v151
	v_cmp_lt_u32_e64 s[0:1], s91, v152
	v_cmp_lt_u32_e64 s[2:3], s91, v153
	v_cndmask_b32_e64 v48, v48, v230, s[94:95]
	v_cndmask_b32_e64 v49, v49, v230, s[86:87]
	v_cndmask_b32_e64 v50, v50, v230, s[0:1]
	v_cndmask_b32_e64 v51, v51, v230, s[2:3]
	v_sub_u32_e32 v150, 64, v200
	v_sub_u32_e32 v151, 0x41, v200
	v_sub_u32_e32 v152, 0x42, v200
	v_sub_u32_e32 v153, 0x43, v200
	v_cmp_lt_u32_e64 s[94:95], s91, v150
	s_waitcnt lgkmcnt(0)
	s_add_i32 s93, s76, 0x400
	s_mov_b32 m0, s14
	v_add_u32_e32 v164, s93, v231
	v_med3_i32 v164, v164, 0, s40
	v_lshl_or_b32 v164, v164, 7, v222
	global_load_lds_dwordx4 v164, s[24:25]
	s_add_i32 m0, s14, 0x400
	v_add_u32_e32 v165, s93, v232
	v_med3_i32 v165, v165, 0, s40
	v_lshl_or_b32 v165, v165, 7, v222
	global_load_lds_dwordx4 v165, s[24:25]
	s_waitcnt vmcnt(8)
	v_add_u32_e32 v154, s15, v225
	v_add_u32_e32 v155, s15, v226
	v_add_u32_e32 v156, s15, v227
	v_add_u32_e32 v157, s15, v228
	ds_read_b64_tr_b16 v[88:89], v154
	ds_read_b64_tr_b16 v[90:91], v155
	ds_read_b64_tr_b16 v[92:93], v156
	ds_read_b64_tr_b16 v[94:95], v157
	v_mfma_f32_16x16x16_bf16 v[96:99], v[202:203], v[12:13], v[96:99]
	v_mfma_f32_16x16x16_bf16 v[100:103], v[204:205], v[12:13], v[100:103]
	v_mfma_f32_16x16x16_bf16 v[104:107], v[206:207], v[12:13], v[104:107]
	v_mfma_f32_16x16x16_bf16 v[108:111], v[208:209], v[12:13], v[108:111]
	v_cmp_lt_u32_e64 s[86:87], s91, v151
	v_cmp_lt_u32_e64 s[0:1], s91, v152
	v_cmp_lt_u32_e64 s[2:3], s91, v153
	v_cndmask_b32_e64 v52, v52, v230, s[94:95]
	v_cndmask_b32_e64 v53, v53, v230, s[86:87]
	v_cndmask_b32_e64 v54, v54, v230, s[0:1]
	v_cndmask_b32_e64 v55, v55, v230, s[2:3]
	v_sub_u32_e32 v150, 0x50, v200
	v_sub_u32_e32 v151, 0x51, v200
	v_sub_u32_e32 v152, 0x52, v200
	v_sub_u32_e32 v153, 0x53, v200
	v_cmp_lt_u32_e64 s[94:95], s91, v150
	v_cmp_lt_u32_e64 s[86:87], s91, v151
	v_cmp_lt_u32_e64 s[0:1], s91, v152
	v_cmp_lt_u32_e64 s[2:3], s91, v153
	v_cndmask_b32_e64 v56, v56, v230, s[94:95]
	v_cndmask_b32_e64 v57, v57, v230, s[86:87]
	v_cndmask_b32_e64 v58, v58, v230, s[0:1]
	v_cndmask_b32_e64 v59, v59, v230, s[2:3]
	v_sub_u32_e32 v150, 0x60, v200
	v_sub_u32_e32 v151, 0x61, v200
	v_sub_u32_e32 v152, 0x62, v200
	v_sub_u32_e32 v153, 0x63, v200
	v_cmp_lt_u32_e64 s[94:95], s91, v150
	v_cmp_lt_u32_e64 s[86:87], s91, v151
	v_cmp_lt_u32_e64 s[0:1], s91, v152
	v_cmp_lt_u32_e64 s[2:3], s91, v153
	v_cndmask_b32_e64 v60, v60, v230, s[94:95]
	v_cndmask_b32_e64 v61, v61, v230, s[86:87]
	v_cndmask_b32_e64 v62, v62, v230, s[0:1]
	v_cndmask_b32_e64 v63, v63, v230, s[2:3]
	s_waitcnt lgkmcnt(0)
	s_add_i32 s93, s8, 0xfffffc00
	s_mov_b32 m0, s15
	v_add_u32_e32 v164, s93, v231
	v_med3_i32 v164, v164, 0, s40
	v_lshl_or_b32 v164, v164, 7, v222
	global_load_lds_dwordx4 v164, s[24:25]
	s_add_i32 m0, s15, 0x400
	v_add_u32_e32 v165, s93, v232
	v_med3_i32 v165, v165, 0, s40
	v_lshl_or_b32 v165, v165, 7, v222
	global_load_lds_dwordx4 v165, s[24:25]
	s_waitcnt vmcnt(8)
	v_add_u32_e32 v154, s16, v225
	v_add_u32_e32 v155, s16, v226
	v_add_u32_e32 v156, s16, v227
	v_add_u32_e32 v157, s16, v228
	ds_read_b64_tr_b16 v[202:203], v154
	ds_read_b64_tr_b16 v[204:205], v155
	ds_read_b64_tr_b16 v[206:207], v156
	ds_read_b64_tr_b16 v[208:209], v157
	v_mfma_f32_16x16x16_bf16 v[96:99], v[88:89], v[16:17], v[96:99]
	v_mfma_f32_16x16x16_bf16 v[100:103], v[90:91], v[16:17], v[100:103]
	v_mfma_f32_16x16x16_bf16 v[104:107], v[92:93], v[16:17], v[104:107]
	v_mfma_f32_16x16x16_bf16 v[108:111], v[94:95], v[16:17], v[108:111]
	v_sub_u32_e32 v150, 0x70, v200
	v_sub_u32_e32 v151, 0x71, v200
	v_sub_u32_e32 v152, 0x72, v200
	v_sub_u32_e32 v153, 0x73, v200
	v_cmp_lt_u32_e64 s[94:95], s91, v150
	v_cmp_lt_u32_e64 s[86:87], s91, v151
	v_cmp_lt_u32_e64 s[0:1], s91, v152
	v_cmp_lt_u32_e64 s[2:3], s91, v153
	v_cndmask_b32_e64 v64, v64, v230, s[94:95]
	v_cndmask_b32_e64 v65, v65, v230, s[86:87]
	v_cndmask_b32_e64 v66, v66, v230, s[0:1]
	v_cndmask_b32_e64 v67, v67, v230, s[2:3]
	v_sub_u32_e32 v150, 0x80, v200
	v_sub_u32_e32 v151, 0x81, v200
	v_sub_u32_e32 v152, 0x82, v200
	v_sub_u32_e32 v153, 0x83, v200
	v_cmp_lt_u32_e64 s[94:95], s91, v150
	v_cmp_lt_u32_e64 s[86:87], s91, v151
	v_cmp_lt_u32_e64 s[0:1], s91, v152
	v_cmp_lt_u32_e64 s[2:3], s91, v153
	v_cndmask_b32_e64 v68, v68, v230, s[94:95]
	v_cndmask_b32_e64 v69, v69, v230, s[86:87]
	v_cndmask_b32_e64 v70, v70, v230, s[0:1]
	v_cndmask_b32_e64 v71, v71, v230, s[2:3]
	v_max3_f32 v186, v36, v37, v38
	v_max3_f32 v186, v186, v39, v40
	v_max3_f32 v186, v186, v41, v42
	v_max3_f32 v186, v186, v43, v44
	v_max3_f32 v186, v186, v45, v46
	v_max3_f32 v186, v186, v47, v48
	v_max3_f32 v186, v186, v49, v50
	s_waitcnt lgkmcnt(0)
	s_add_i32 s93, s8, 0xfffffd00
	s_mov_b32 m0, s16
	v_add_u32_e32 v164, s93, v231
	v_med3_i32 v164, v164, 0, s40
	v_lshl_or_b32 v164, v164, 7, v222
	global_load_lds_dwordx4 v164, s[24:25]
	s_add_i32 m0, s16, 0x400
	v_add_u32_e32 v165, s93, v232
	v_med3_i32 v165, v165, 0, s40
	v_lshl_or_b32 v165, v165, 7, v222
	global_load_lds_dwordx4 v165, s[24:25]
	s_waitcnt vmcnt(8)
	v_add_u32_e32 v154, s12, v225
	v_add_u32_e32 v155, s12, v226
	v_add_u32_e32 v156, s12, v227
	v_add_u32_e32 v157, s12, v228
	ds_read_b64_tr_b16 v[88:89], v154
	ds_read_b64_tr_b16 v[90:91], v155
	ds_read_b64_tr_b16 v[92:93], v156
	ds_read_b64_tr_b16 v[94:95], v157
	v_mfma_f32_16x16x16_bf16 v[96:99], v[202:203], v[20:21], v[96:99]
	v_mfma_f32_16x16x16_bf16 v[100:103], v[204:205], v[20:21], v[100:103]
	v_mfma_f32_16x16x16_bf16 v[104:107], v[206:207], v[20:21], v[104:107]
	v_mfma_f32_16x16x16_bf16 v[108:111], v[208:209], v[20:21], v[108:111]
	v_max3_f32 v186, v186, v51, v52
	v_max3_f32 v186, v186, v53, v54
	v_max3_f32 v186, v186, v55, v56
	v_max3_f32 v186, v186, v57, v58
	v_max3_f32 v186, v186, v59, v60
	v_max3_f32 v186, v186, v61, v62
	v_max3_f32 v186, v186, v63, v64
	v_max3_f32 v186, v186, v65, v66
	v_max3_f32 v186, v186, v67, v68
	v_max3_f32 v186, v186, v69, v70
	v_max_f32_e32 v186, v186, v71
	v_mov_b32_e32 v146, v186
	s_nop 1
	v_permlane16_swap_b32_e32 v186, v146
	v_max_f32_e32 v186, v186, v146
	v_mov_b32_e32 v146, v186
	s_nop 1
	v_permlane32_swap_b32_e32 v186, v146
	v_max_f32_e32 v186, v186, v146
	v_pk_add_f32 v[36:37], v[36:37], v[186:187] op_sel_hi:[1,0] neg_lo:[0,1] neg_hi:[0,1]
	v_pk_add_f32 v[38:39], v[38:39], v[186:187] op_sel_hi:[1,0] neg_lo:[0,1] neg_hi:[0,1]
	v_pk_add_f32 v[40:41], v[40:41], v[186:187] op_sel_hi:[1,0] neg_lo:[0,1] neg_hi:[0,1]
	v_pk_add_f32 v[42:43], v[42:43], v[186:187] op_sel_hi:[1,0] neg_lo:[0,1] neg_hi:[0,1]
	v_exp_f32_e32 v36, v36
	v_exp_f32_e32 v37, v37
	v_exp_f32_e32 v38, v38
	v_exp_f32_e32 v39, v39
	v_pk_add_f32 v[44:45], v[44:45], v[186:187] op_sel_hi:[1,0] neg_lo:[0,1] neg_hi:[0,1]
	v_pk_add_f32 v[46:47], v[46:47], v[186:187] op_sel_hi:[1,0] neg_lo:[0,1] neg_hi:[0,1]
	v_exp_f32_e32 v40, v40
	v_exp_f32_e32 v41, v41
	v_exp_f32_e32 v42, v42
	v_exp_f32_e32 v43, v43
	s_waitcnt lgkmcnt(0)
	s_add_i32 s93, s8, 0xfffffe00
	s_mov_b32 m0, s12
	v_add_u32_e32 v164, s93, v231
	v_med3_i32 v164, v164, 0, s40
	v_lshl_or_b32 v164, v164, 7, v222
	global_load_lds_dwordx4 v164, s[24:25]
	s_add_i32 m0, s12, 0x400
	v_add_u32_e32 v165, s93, v232
	v_med3_i32 v165, v165, 0, s40
	v_lshl_or_b32 v165, v165, 7, v222
	global_load_lds_dwordx4 v165, s[24:25]
	s_waitcnt vmcnt(8)
	v_add_u32_e32 v154, s13, v225
	v_add_u32_e32 v155, s13, v226
	v_add_u32_e32 v156, s13, v227
	v_add_u32_e32 v157, s13, v228
	ds_read_b64_tr_b16 v[202:203], v154
	ds_read_b64_tr_b16 v[204:205], v155
	ds_read_b64_tr_b16 v[206:207], v156
	ds_read_b64_tr_b16 v[208:209], v157
	v_mfma_f32_16x16x16_bf16 v[96:99], v[88:89], v[24:25], v[96:99]
	v_mfma_f32_16x16x16_bf16 v[100:103], v[90:91], v[24:25], v[100:103]
	v_mfma_f32_16x16x16_bf16 v[104:107], v[92:93], v[24:25], v[104:107]
	v_mfma_f32_16x16x16_bf16 v[108:111], v[94:95], v[24:25], v[108:111]
	v_pk_add_f32 v[48:49], v[48:49], v[186:187] op_sel_hi:[1,0] neg_lo:[0,1] neg_hi:[0,1]
	v_pk_add_f32 v[50:51], v[50:51], v[186:187] op_sel_hi:[1,0] neg_lo:[0,1] neg_hi:[0,1]
	v_exp_f32_e32 v44, v44
	v_exp_f32_e32 v45, v45
	v_exp_f32_e32 v46, v46
	v_exp_f32_e32 v47, v47
	v_pk_add_f32 v[52:53], v[52:53], v[186:187] op_sel_hi:[1,0] neg_lo:[0,1] neg_hi:[0,1]
	v_pk_add_f32 v[54:55], v[54:55], v[186:187] op_sel_hi:[1,0] neg_lo:[0,1] neg_hi:[0,1]
	v_exp_f32_e32 v48, v48
	v_exp_f32_e32 v49, v49
	v_exp_f32_e32 v50, v50
	v_exp_f32_e32 v51, v51
	v_pk_add_f32 v[56:57], v[56:57], v[186:187] op_sel_hi:[1,0] neg_lo:[0,1] neg_hi:[0,1]
	v_pk_add_f32 v[58:59], v[58:59], v[186:187] op_sel_hi:[1,0] neg_lo:[0,1] neg_hi:[0,1]
	v_exp_f32_e32 v52, v52
	v_exp_f32_e32 v53, v53
	v_exp_f32_e32 v54, v54
	v_exp_f32_e32 v55, v55
	v_pk_add_f32 v[60:61], v[60:61], v[186:187] op_sel_hi:[1,0] neg_lo:[0,1] neg_hi:[0,1]
	v_pk_add_f32 v[62:63], v[62:63], v[186:187] op_sel_hi:[1,0] neg_lo:[0,1] neg_hi:[0,1]
	v_exp_f32_e32 v56, v56
	v_exp_f32_e32 v57, v57
	v_exp_f32_e32 v58, v58
	v_exp_f32_e32 v59, v59
	v_pk_add_f32 v[64:65], v[64:65], v[186:187] op_sel_hi:[1,0] neg_lo:[0,1] neg_hi:[0,1]
	v_pk_add_f32 v[66:67], v[66:67], v[186:187] op_sel_hi:[1,0] neg_lo:[0,1] neg_hi:[0,1]
	v_exp_f32_e32 v60, v60
	v_exp_f32_e32 v61, v61
	v_exp_f32_e32 v62, v62
	v_exp_f32_e32 v63, v63
	v_pk_add_f32 v[68:69], v[68:69], v[186:187] op_sel_hi:[1,0] neg_lo:[0,1] neg_hi:[0,1]
	s_waitcnt lgkmcnt(0)
	s_add_i32 s93, s8, 0xffffff00
	s_mov_b32 m0, s13
	v_add_u32_e32 v164, s93, v231
	v_med3_i32 v164, v164, 0, s40
	v_lshl_or_b32 v164, v164, 7, v222
	global_load_lds_dwordx4 v164, s[24:25]
	s_add_i32 m0, s13, 0x400
	v_add_u32_e32 v165, s93, v232
	v_med3_i32 v165, v165, 0, s40
	v_lshl_or_b32 v165, v165, 7, v222
	global_load_lds_dwordx4 v165, s[24:25]
	s_waitcnt vmcnt(8)
	v_add_u32_e32 v154, s14, v225
	v_add_u32_e32 v155, s14, v226
	v_add_u32_e32 v156, s14, v227
	v_add_u32_e32 v157, s14, v228
	ds_read_b64_tr_b16 v[88:89], v154
	ds_read_b64_tr_b16 v[90:91], v155
	ds_read_b64_tr_b16 v[92:93], v156
	ds_read_b64_tr_b16 v[94:95], v157
	v_mfma_f32_16x16x16_bf16 v[96:99], v[202:203], v[28:29], v[96:99]
	v_mfma_f32_16x16x16_bf16 v[100:103], v[204:205], v[28:29], v[100:103]
	v_mfma_f32_16x16x16_bf16 v[104:107], v[206:207], v[28:29], v[104:107]
	v_mfma_f32_16x16x16_bf16 v[108:111], v[208:209], v[28:29], v[108:111]
	v_pk_add_f32 v[70:71], v[70:71], v[186:187] op_sel_hi:[1,0] neg_lo:[0,1] neg_hi:[0,1]
	v_exp_f32_e32 v64, v64
	v_exp_f32_e32 v65, v65
	v_exp_f32_e32 v66, v66
	v_exp_f32_e32 v67, v67
	v_exp_f32_e32 v68, v68
	v_exp_f32_e32 v69, v69
	v_exp_f32_e32 v70, v70
	v_exp_f32_e32 v71, v71
	s_nop 0
	v_pk_add_f32 v[146:147], v[36:37], v[38:39]
	v_pk_add_f32 v[148:149], v[40:41], v[42:43]
	v_pk_add_f32 v[146:147], v[146:147], v[44:45]
	v_pk_add_f32 v[148:149], v[148:149], v[46:47]
	v_pk_add_f32 v[146:147], v[146:147], v[48:49]
	v_pk_add_f32 v[148:149], v[148:149], v[50:51]
	v_pk_add_f32 v[146:147], v[146:147], v[52:53]
	v_pk_add_f32 v[148:149], v[148:149], v[54:55]
	v_pk_add_f32 v[146:147], v[146:147], v[56:57]
	v_pk_add_f32 v[148:149], v[148:149], v[58:59]
	v_pk_add_f32 v[146:147], v[146:147], v[60:61]
	v_pk_add_f32 v[148:149], v[148:149], v[62:63]
	v_pk_add_f32 v[146:147], v[146:147], v[64:65]
	v_pk_add_f32 v[148:149], v[148:149], v[66:67]
	v_pk_add_f32 v[146:147], v[146:147], v[68:69]
	v_pk_add_f32 v[148:149], v[148:149], v[70:71]
	s_nop 0
	v_pk_add_f32 v[146:147], v[146:147], v[148:149]
	s_nop 0
	v_add_f32_e32 v187, v146, v147
	v_cvt_pk_bf16_f32 v36, v36, v37
	s_waitcnt lgkmcnt(0)
	s_add_i32 s93, s8, 0
	s_mov_b32 m0, s14
	v_add_u32_e32 v164, s93, v231
	v_med3_i32 v164, v164, 0, s40
	v_lshl_or_b32 v164, v164, 7, v222
	global_load_lds_dwordx4 v164, s[24:25]
	s_add_i32 m0, s14, 0x400
	v_add_u32_e32 v165, s93, v232
	v_med3_i32 v165, v165, 0, s40
	v_lshl_or_b32 v165, v165, 7, v222
	global_load_lds_dwordx4 v165, s[24:25]
	s_waitcnt vmcnt(8)
	v_add_u32_e32 v72, s15, v225
	v_add_u32_e32 v73, s15, v226
	v_add_u32_e32 v74, s15, v227
	v_add_u32_e32 v75, s15, v228
	ds_read_b64_tr_b16 v[202:203], v72
	ds_read_b64_tr_b16 v[204:205], v73
	ds_read_b64_tr_b16 v[206:207], v74
	ds_read_b64_tr_b16 v[208:209], v75
	v_mfma_f32_16x16x16_bf16 v[96:99], v[88:89], v[32:33], v[96:99]
	v_mfma_f32_16x16x16_bf16 v[100:103], v[90:91], v[32:33], v[100:103]
	v_mfma_f32_16x16x16_bf16 v[104:107], v[92:93], v[32:33], v[104:107]
	v_mfma_f32_16x16x16_bf16 v[108:111], v[94:95], v[32:33], v[108:111]
	v_cvt_pk_bf16_f32 v37, v38, v39
	v_cvt_pk_bf16_f32 v40, v40, v41
	v_cvt_pk_bf16_f32 v41, v42, v43
	v_cvt_pk_bf16_f32 v44, v44, v45
	v_cvt_pk_bf16_f32 v45, v46, v47
	v_cvt_pk_bf16_f32 v48, v48, v49
	v_cvt_pk_bf16_f32 v49, v50, v51
	v_cvt_pk_bf16_f32 v52, v52, v53
	v_cvt_pk_bf16_f32 v53, v54, v55
	v_cvt_pk_bf16_f32 v56, v56, v57
	v_cvt_pk_bf16_f32 v57, v58, v59
	v_cvt_pk_bf16_f32 v60, v60, v61
	v_cvt_pk_bf16_f32 v61, v62, v63
	v_cvt_pk_bf16_f32 v64, v64, v65
	v_cvt_pk_bf16_f32 v65, v66, v67
	v_cvt_pk_bf16_f32 v68, v68, v69
	v_cvt_pk_bf16_f32 v69, v70, v71
	v_mov_b32_e32 v146, v187
	s_nop 1
	v_permlane16_swap_b32_e32 v187, v146
	v_add_f32_e32 v187, v187, v146
	v_mov_b32_e32 v146, v187
	s_nop 1
	v_permlane32_swap_b32_e32 v187, v146
	v_add_f32_e32 v187, v187, v146
	s_waitcnt lgkmcnt(0)
	s_add_i32 s93, s8, 0x100
	s_mov_b32 m0, s15
	v_add_u32_e32 v164, s93, v231
	v_med3_i32 v164, v164, 0, s40
	v_lshl_or_b32 v164, v164, 7, v222
	global_load_lds_dwordx4 v164, s[24:25]
	s_add_i32 m0, s15, 0x400
	v_add_u32_e32 v165, s93, v232
	v_med3_i32 v165, v165, 0, s40
	v_lshl_or_b32 v165, v165, 7, v222
	global_load_lds_dwordx4 v165, s[24:25]
	s_waitcnt vmcnt(8)
	v_add_u32_e32 v72, s16, v225
	v_add_u32_e32 v73, s16, v226
	v_add_u32_e32 v74, s16, v227
	v_add_u32_e32 v75, s16, v228
	ds_read_b64_tr_b16 v[88:89], v72
	ds_read_b64_tr_b16 v[90:91], v73
	ds_read_b64_tr_b16 v[92:93], v74
	ds_read_b64_tr_b16 v[94:95], v75
	v_mfma_f32_16x16x16_bf16 v[112:115], v[202:203], v[36:37], 0
	v_mfma_f32_16x16x16_bf16 v[116:119], v[204:205], v[36:37], 0
	v_mfma_f32_16x16x16_bf16 v[120:123], v[206:207], v[36:37], 0
	v_mfma_f32_16x16x16_bf16 v[124:127], v[208:209], v[36:37], 0
	s_waitcnt lgkmcnt(0)
	v_max_f32_e32 v146, v144, v184
	v_sub_f32_e32 v148, v144, v146
	v_sub_f32_e32 v150, v184, v146
	v_exp_f32_e32 v148, v148
	v_exp_f32_e32 v150, v150
	v_mov_b32_e32 v184, v146
	v_mul_f32_e32 v185, v185, v150
	v_fmac_f32_e32 v185, v145, v148
	v_pk_mul_f32 v[96:97], v[150:151], v[96:97] op_sel_hi:[0,1]
	v_pk_mul_f32 v[98:99], v[150:151], v[98:99] op_sel_hi:[0,1]
	v_pk_mul_f32 v[100:101], v[150:151], v[100:101] op_sel_hi:[0,1]
	s_waitcnt lgkmcnt(0)
	s_add_i32 s93, s8, 0x200
	s_mov_b32 m0, s16
	v_add_u32_e32 v164, s93, v231
	v_med3_i32 v164, v164, 0, s40
	v_lshl_or_b32 v164, v164, 7, v222
	global_load_lds_dwordx4 v164, s[24:25]
	s_add_i32 m0, s16, 0x400
	v_add_u32_e32 v165, s93, v232
	v_med3_i32 v165, v165, 0, s40
	v_lshl_or_b32 v165, v165, 7, v222
	global_load_lds_dwordx4 v165, s[24:25]
	s_waitcnt vmcnt(8)
	v_add_u32_e32 v72, s12, v225
	v_add_u32_e32 v73, s12, v226
	v_add_u32_e32 v74, s12, v227
	v_add_u32_e32 v75, s12, v228
	ds_read_b64_tr_b16 v[202:203], v72
	ds_read_b64_tr_b16 v[204:205], v73
	ds_read_b64_tr_b16 v[206:207], v74
	ds_read_b64_tr_b16 v[208:209], v75
	v_mfma_f32_16x16x16_bf16 v[112:115], v[88:89], v[40:41], v[112:115]
	v_mfma_f32_16x16x16_bf16 v[116:119], v[90:91], v[40:41], v[116:119]
	v_mfma_f32_16x16x16_bf16 v[120:123], v[92:93], v[40:41], v[120:123]
	v_mfma_f32_16x16x16_bf16 v[124:127], v[94:95], v[40:41], v[124:127]
	v_pk_mul_f32 v[102:103], v[150:151], v[102:103] op_sel_hi:[0,1]
	v_pk_mul_f32 v[104:105], v[150:151], v[104:105] op_sel_hi:[0,1]
	v_pk_mul_f32 v[106:107], v[150:151], v[106:107] op_sel_hi:[0,1]
	v_pk_mul_f32 v[108:109], v[150:151], v[108:109] op_sel_hi:[0,1]
	v_pk_mul_f32 v[110:111], v[150:151], v[110:111] op_sel_hi:[0,1]
	v_pk_fma_f32 v[96:97], v[148:149], v[128:129], v[96:97] op_sel_hi:[0,1,1]
	v_pk_fma_f32 v[98:99], v[148:149], v[130:131], v[98:99] op_sel_hi:[0,1,1]
	v_pk_fma_f32 v[100:101], v[148:149], v[132:133], v[100:101] op_sel_hi:[0,1,1]
	v_pk_fma_f32 v[102:103], v[148:149], v[134:135], v[102:103] op_sel_hi:[0,1,1]
	v_pk_fma_f32 v[104:105], v[148:149], v[136:137], v[104:105] op_sel_hi:[0,1,1]
	v_pk_fma_f32 v[106:107], v[148:149], v[138:139], v[106:107] op_sel_hi:[0,1,1]
	v_pk_fma_f32 v[108:109], v[148:149], v[140:141], v[108:109] op_sel_hi:[0,1,1]
	s_waitcnt lgkmcnt(0)
	s_add_i32 s93, s8, 0x300
	s_mov_b32 m0, s12
	v_add_u32_e32 v164, s93, v231
	v_med3_i32 v164, v164, 0, s40
	v_lshl_or_b32 v164, v164, 7, v222
	global_load_lds_dwordx4 v164, s[24:25]
	s_add_i32 m0, s12, 0x400
	v_add_u32_e32 v165, s93, v232
	v_med3_i32 v165, v165, 0, s40
	v_lshl_or_b32 v165, v165, 7, v222
	global_load_lds_dwordx4 v165, s[24:25]
	s_waitcnt vmcnt(8)
	v_add_u32_e32 v72, s13, v225
	v_add_u32_e32 v73, s13, v226
	v_add_u32_e32 v74, s13, v227
	v_add_u32_e32 v75, s13, v228
	ds_read_b64_tr_b16 v[88:89], v72
	ds_read_b64_tr_b16 v[90:91], v73
	ds_read_b64_tr_b16 v[92:93], v74
	ds_read_b64_tr_b16 v[94:95], v75
	v_mfma_f32_16x16x16_bf16 v[112:115], v[202:203], v[44:45], v[112:115]
	v_mfma_f32_16x16x16_bf16 v[116:119], v[204:205], v[44:45], v[116:119]
	v_mfma_f32_16x16x16_bf16 v[120:123], v[206:207], v[44:45], v[120:123]
	v_mfma_f32_16x16x16_bf16 v[124:127], v[208:209], v[44:45], v[124:127]
	v_pk_fma_f32 v[110:111], v[148:149], v[142:143], v[110:111] op_sel_hi:[0,1,1]
	v_div_scale_f32 v147, s[94:95], v185, v185, 1.0
	v_rcp_f32_e32 v148, v147
	v_div_scale_f32 v149, vcc, 1.0, v185, 1.0
	v_fma_f32 v150, -v147, v148, 1.0
	v_fmac_f32_e32 v148, v150, v148
	v_mul_f32_e32 v150, v149, v148
	v_fma_f32 v151, -v147, v150, v149
	v_fmac_f32_e32 v150, v151, v148
	v_fma_f32 v147, -v147, v150, v149
	s_nop 1
	v_div_fmas_f32 v147, v147, v148, v150
	s_waitcnt lgkmcnt(0)
	s_add_i32 s93, s8, 0x400
	s_mov_b32 m0, s13
	v_add_u32_e32 v164, s93, v231
	v_med3_i32 v164, v164, 0, s40
	v_lshl_or_b32 v164, v164, 7, v222
	global_load_lds_dwordx4 v164, s[24:25]
	s_add_i32 m0, s13, 0x400
	v_add_u32_e32 v165, s93, v232
	v_med3_i32 v165, v165, 0, s40
	v_lshl_or_b32 v165, v165, 7, v222
	global_load_lds_dwordx4 v165, s[24:25]
	s_waitcnt vmcnt(8)
	v_add_u32_e32 v72, s14, v225
	v_add_u32_e32 v73, s14, v226
	v_add_u32_e32 v74, s14, v227
	v_add_u32_e32 v75, s14, v228
	ds_read_b64_tr_b16 v[202:203], v72
	ds_read_b64_tr_b16 v[204:205], v73
	ds_read_b64_tr_b16 v[206:207], v74
	ds_read_b64_tr_b16 v[208:209], v75
	v_mfma_f32_16x16x16_bf16 v[112:115], v[88:89], v[48:49], v[112:115]
	v_mfma_f32_16x16x16_bf16 v[116:119], v[90:91], v[48:49], v[116:119]
	v_mfma_f32_16x16x16_bf16 v[120:123], v[92:93], v[48:49], v[120:123]
	v_mfma_f32_16x16x16_bf16 v[124:127], v[94:95], v[48:49], v[124:127]
	v_div_fixup_f32 v152, v147, v185, 1.0
	v_pk_mul_f32 v[96:97], v[152:153], v[96:97] op_sel_hi:[0,1]
	v_pk_mul_f32 v[98:99], v[152:153], v[98:99] op_sel_hi:[0,1]
	v_pk_mul_f32 v[100:101], v[152:153], v[100:101] op_sel_hi:[0,1]
	v_pk_mul_f32 v[102:103], v[152:153], v[102:103] op_sel_hi:[0,1]
	v_pk_mul_f32 v[104:105], v[152:153], v[104:105] op_sel_hi:[0,1]
	v_pk_mul_f32 v[106:107], v[152:153], v[106:107] op_sel_hi:[0,1]
	v_pk_mul_f32 v[108:109], v[152:153], v[108:109] op_sel_hi:[0,1]
	v_pk_mul_f32 v[110:111], v[152:153], v[110:111] op_sel_hi:[0,1]
	v_mul_f32_e32 v155, v97, v97
	v_mul_f32_e32 v156, v99, v99
	v_fmac_f32_e32 v155, v96, v96
	s_waitcnt lgkmcnt(0)
	s_add_i32 s93, s79, 0
	s_mov_b32 m0, s14
	v_add_u32_e32 v164, s93, v162
	v_lshl_or_b32 v164, v164, 7, v220
	global_load_lds_dwordx4 v164, s[30:31]
	s_add_i32 m0, s14, 0x400
	v_add_u32_e32 v165, s93, v163
	v_lshl_or_b32 v165, v165, 7, v221
	global_load_lds_dwordx4 v165, s[30:31]
	s_waitcnt vmcnt(8)
	v_add_u32_e32 v72, s15, v225
	v_add_u32_e32 v73, s15, v226
	v_add_u32_e32 v74, s15, v227
	v_add_u32_e32 v75, s15, v228
	ds_read_b64_tr_b16 v[88:89], v72
	ds_read_b64_tr_b16 v[90:91], v73
	ds_read_b64_tr_b16 v[92:93], v74
	ds_read_b64_tr_b16 v[94:95], v75
	v_mfma_f32_16x16x16_bf16 v[112:115], v[202:203], v[52:53], v[112:115]
	v_mfma_f32_16x16x16_bf16 v[116:119], v[204:205], v[52:53], v[116:119]
	v_mfma_f32_16x16x16_bf16 v[120:123], v[206:207], v[52:53], v[120:123]
	v_mfma_f32_16x16x16_bf16 v[124:127], v[208:209], v[52:53], v[124:127]
	v_fmac_f32_e32 v156, v98, v98
	v_add_f32_e32 v154, v155, v156
	v_mul_f32_e32 v155, v101, v101
	v_mul_f32_e32 v156, v103, v103
	v_fmac_f32_e32 v155, v100, v100
	v_fmac_f32_e32 v156, v102, v102
	v_add_f32_e32 v155, v155, v156
	v_add_f32_e32 v154, v154, v155
	v_mul_f32_e32 v155, v105, v105
	v_mul_f32_e32 v156, v107, v107
	v_fmac_f32_e32 v155, v104, v104
	v_fmac_f32_e32 v156, v106, v106
	s_waitcnt lgkmcnt(0)
	s_add_i32 s93, s79, 16
	s_mov_b32 m0, s15
	v_add_u32_e32 v164, s93, v162
	v_lshl_or_b32 v164, v164, 7, v220
	global_load_lds_dwordx4 v164, s[30:31]
	s_add_i32 m0, s15, 0x400
	v_add_u32_e32 v165, s93, v163
	v_lshl_or_b32 v165, v165, 7, v221
	global_load_lds_dwordx4 v165, s[30:31]
	s_waitcnt vmcnt(8)
	v_add_u32_e32 v72, s16, v225
	v_add_u32_e32 v73, s16, v226
	v_add_u32_e32 v74, s16, v227
	v_add_u32_e32 v75, s16, v228
	ds_read_b64_tr_b16 v[202:203], v72
	ds_read_b64_tr_b16 v[204:205], v73
	ds_read_b64_tr_b16 v[206:207], v74
	ds_read_b64_tr_b16 v[208:209], v75
	v_mfma_f32_16x16x16_bf16 v[112:115], v[88:89], v[56:57], v[112:115]
	v_mfma_f32_16x16x16_bf16 v[116:119], v[90:91], v[56:57], v[116:119]
	v_mfma_f32_16x16x16_bf16 v[120:123], v[92:93], v[56:57], v[120:123]
	v_mfma_f32_16x16x16_bf16 v[124:127], v[94:95], v[56:57], v[124:127]
	v_add_f32_e32 v155, v155, v156
	v_add_f32_e32 v154, v154, v155
	v_mul_f32_e32 v155, v109, v109
	v_mul_f32_e32 v156, v111, v111
	v_fmac_f32_e32 v155, v108, v108
	v_fmac_f32_e32 v156, v110, v110
	v_add_f32_e32 v155, v155, v156
	v_add_f32_e32 v154, v154, v155
	v_cvt_pk_bf16_f32 v96, v96, v97
	v_cvt_pk_bf16_f32 v97, v98, v99
	v_cvt_pk_bf16_f32 v100, v100, v101
	v_cvt_pk_bf16_f32 v101, v102, v103
	s_waitcnt lgkmcnt(0)
	s_add_i32 s93, s79, 0xffffffc0
	s_mov_b32 m0, s16
	v_add_u32_e32 v164, s93, v162
	v_med3_i32 v164, v164, 0, s41
	v_lshl_or_b32 v164, v164, 7, v220
	global_load_lds_dwordx4 v164, s[34:35]
	s_add_i32 m0, s16, 0x400
	v_add_u32_e32 v165, s93, v163
	v_med3_i32 v165, v165, 0, s41
	v_lshl_or_b32 v165, v165, 7, v221
	global_load_lds_dwordx4 v165, s[34:35]
	s_waitcnt vmcnt(8)
	v_add_u32_e32 v72, s12, v225
	v_add_u32_e32 v73, s12, v226
	v_add_u32_e32 v74, s12, v227
	v_add_u32_e32 v75, s12, v228
	ds_read_b64_tr_b16 v[88:89], v72
	ds_read_b64_tr_b16 v[90:91], v73
	ds_read_b64_tr_b16 v[92:93], v74
	ds_read_b64_tr_b16 v[94:95], v75
	v_mfma_f32_16x16x16_bf16 v[112:115], v[202:203], v[60:61], v[112:115]
	v_mfma_f32_16x16x16_bf16 v[116:119], v[204:205], v[60:61], v[116:119]
	v_mfma_f32_16x16x16_bf16 v[120:123], v[206:207], v[60:61], v[120:123]
	v_mfma_f32_16x16x16_bf16 v[124:127], v[208:209], v[60:61], v[124:127]
	v_cvt_pk_bf16_f32 v104, v104, v105
	v_cvt_pk_bf16_f32 v105, v106, v107
	v_cvt_pk_bf16_f32 v108, v108, v109
	v_cvt_pk_bf16_f32 v109, v110, v111
	v_add_u32_e32 v157, s42, v188
	s_lshl_b32 s90, s43, 7
	v_lshlrev_b32_e32 v158, 11, v157
	v_add3_u32 v158, v158, s90, v233
	v_mov_b32_e32 v76, v96
	v_mov_b32_e32 v77, v97
	v_mov_b32_e32 v78, v100
	v_mov_b32_e32 v79, v101
	s_waitcnt lgkmcnt(0)
	s_add_i32 s93, s79, 0xffffffd0
	s_mov_b32 m0, s12
	v_add_u32_e32 v164, s93, v162
	v_med3_i32 v164, v164, 0, s41
	v_lshl_or_b32 v164, v164, 7, v220
	global_load_lds_dwordx4 v164, s[34:35]
	s_add_i32 m0, s12, 0x400
	v_add_u32_e32 v165, s93, v163
	v_med3_i32 v165, v165, 0, s41
	v_lshl_or_b32 v165, v165, 7, v221
	global_load_lds_dwordx4 v165, s[34:35]
	s_waitcnt vmcnt(8)
	v_add_u32_e32 v72, s13, v225
	v_add_u32_e32 v73, s13, v226
	v_add_u32_e32 v74, s13, v227
	v_add_u32_e32 v75, s13, v228
	ds_read_b64_tr_b16 v[202:203], v72
	ds_read_b64_tr_b16 v[204:205], v73
	ds_read_b64_tr_b16 v[206:207], v74
	ds_read_b64_tr_b16 v[208:209], v75
	v_mfma_f32_16x16x16_bf16 v[112:115], v[88:89], v[64:65], v[112:115]
	v_mfma_f32_16x16x16_bf16 v[116:119], v[90:91], v[64:65], v[116:119]
	v_mfma_f32_16x16x16_bf16 v[120:123], v[92:93], v[64:65], v[120:123]
	v_mfma_f32_16x16x16_bf16 v[124:127], v[94:95], v[64:65], v[124:127]
	s_nop 1
	v_permlane16_swap_b32_e32 v76, v78
	v_permlane16_swap_b32_e32 v77, v79
	v_mov_b32_e32 v80, v104
	v_mov_b32_e32 v81, v105
	v_mov_b32_e32 v82, v108
	v_mov_b32_e32 v83, v109
	s_nop 1
	v_permlane16_swap_b32_e32 v80, v82
	v_permlane16_swap_b32_e32 v81, v83
	v_mov_b32_e32 v155, v154
	s_nop 1
	v_permlane16_swap_b32_e32 v154, v155
	s_waitcnt lgkmcnt(0)
	s_add_i32 s93, s79, 0xffffffe0
	s_mov_b32 m0, s13
	v_add_u32_e32 v164, s93, v162
	v_med3_i32 v164, v164, 0, s41
	v_lshl_or_b32 v164, v164, 7, v220
	global_load_lds_dwordx4 v164, s[34:35]
	s_add_i32 m0, s13, 0x400
	v_add_u32_e32 v165, s93, v163
	v_med3_i32 v165, v165, 0, s41
	v_lshl_or_b32 v165, v165, 7, v221
	global_load_lds_dwordx4 v165, s[34:35]
	v_mfma_f32_16x16x16_bf16 v[112:115], v[202:203], v[68:69], v[112:115]
	v_mfma_f32_16x16x16_bf16 v[116:119], v[204:205], v[68:69], v[116:119]
	v_mfma_f32_16x16x16_bf16 v[120:123], v[206:207], v[68:69], v[120:123]
	v_mfma_f32_16x16x16_bf16 v[124:127], v[208:209], v[68:69], v[124:127]
	v_add_f32_e32 v154, v154, v155
	v_mov_b32_e32 v155, v154
	s_nop 1
	v_permlane32_swap_b32_e32 v154, v155
	v_add_f32_e32 v154, v154, v155
	v_mul_u32_u24_e32 v157, 48, v157
	s_lshl_b32 s90, s43, 2
	v_add_u32_e32 v157, s90, v157
	s_nop 1
	global_store_dwordx4 v158, v[76:79], s[48:49] offset:0
	global_store_dwordx4 v158, v[80:83], s[48:49] offset:64
	s_and_saveexec_b64 s[80:81], s[74:75]
	global_store_dword v157, v154, s[50:51]
	s_mov_b64 exec, s[80:81]
	s_waitcnt lgkmcnt(0)
	v_max_f32_e32 v146, v182, v186
	v_sub_f32_e32 v148, v182, v146
	v_sub_f32_e32 v150, v186, v146
	v_exp_f32_e32 v148, v148
	v_exp_f32_e32 v150, v150
	v_mov_b32_e32 v186, v146
	v_mul_f32_e32 v187, v187, v150
	v_fmac_f32_e32 v187, v183, v148
	v_pk_mul_f32 v[112:113], v[150:151], v[112:113] op_sel_hi:[0,1]
	v_pk_mul_f32 v[114:115], v[150:151], v[114:115] op_sel_hi:[0,1]
	v_pk_mul_f32 v[116:117], v[150:151], v[116:117] op_sel_hi:[0,1]
	v_pk_mul_f32 v[118:119], v[150:151], v[118:119] op_sel_hi:[0,1]
	v_pk_mul_f32 v[120:121], v[150:151], v[120:121] op_sel_hi:[0,1]
	v_pk_mul_f32 v[122:123], v[150:151], v[122:123] op_sel_hi:[0,1]
	v_pk_mul_f32 v[124:125], v[150:151], v[124:125] op_sel_hi:[0,1]
	v_pk_mul_f32 v[126:127], v[150:151], v[126:127] op_sel_hi:[0,1]
	v_pk_fma_f32 v[112:113], v[148:149], v[166:167], v[112:113] op_sel_hi:[0,1,1]
	v_pk_fma_f32 v[114:115], v[148:149], v[168:169], v[114:115] op_sel_hi:[0,1,1]
	v_pk_fma_f32 v[116:117], v[148:149], v[170:171], v[116:117] op_sel_hi:[0,1,1]
	v_pk_fma_f32 v[118:119], v[148:149], v[172:173], v[118:119] op_sel_hi:[0,1,1]
	v_pk_fma_f32 v[120:121], v[148:149], v[174:175], v[120:121] op_sel_hi:[0,1,1]
	v_pk_fma_f32 v[122:123], v[148:149], v[176:177], v[122:123] op_sel_hi:[0,1,1]
	v_pk_fma_f32 v[124:125], v[148:149], v[178:179], v[124:125] op_sel_hi:[0,1,1]
	v_pk_fma_f32 v[126:127], v[148:149], v[180:181], v[126:127] op_sel_hi:[0,1,1]
	v_div_scale_f32 v147, s[94:95], v187, v187, 1.0
	v_rcp_f32_e32 v148, v147
	v_div_scale_f32 v149, vcc, 1.0, v187, 1.0
	v_fma_f32 v150, -v147, v148, 1.0
	v_fmac_f32_e32 v148, v150, v148
	v_mul_f32_e32 v150, v149, v148
	v_fma_f32 v151, -v147, v150, v149
	v_fmac_f32_e32 v150, v151, v148
	v_fma_f32 v147, -v147, v150, v149
	s_nop 1
	v_div_fmas_f32 v147, v147, v148, v150
	v_div_fixup_f32 v152, v147, v187, 1.0
	v_pk_mul_f32 v[112:113], v[152:153], v[112:113] op_sel_hi:[0,1]
	v_pk_mul_f32 v[114:115], v[152:153], v[114:115] op_sel_hi:[0,1]
	v_pk_mul_f32 v[116:117], v[152:153], v[116:117] op_sel_hi:[0,1]
	v_pk_mul_f32 v[118:119], v[152:153], v[118:119] op_sel_hi:[0,1]
	v_pk_mul_f32 v[120:121], v[152:153], v[120:121] op_sel_hi:[0,1]
	v_pk_mul_f32 v[122:123], v[152:153], v[122:123] op_sel_hi:[0,1]
	v_pk_mul_f32 v[124:125], v[152:153], v[124:125] op_sel_hi:[0,1]
	v_pk_mul_f32 v[126:127], v[152:153], v[126:127] op_sel_hi:[0,1]
	v_mul_f32_e32 v155, v113, v113
	v_mul_f32_e32 v156, v115, v115
	v_fmac_f32_e32 v155, v112, v112
	v_fmac_f32_e32 v156, v114, v114
	v_add_f32_e32 v154, v155, v156
	v_mul_f32_e32 v155, v117, v117
	v_mul_f32_e32 v156, v119, v119
	v_fmac_f32_e32 v155, v116, v116
	v_fmac_f32_e32 v156, v118, v118
	v_add_f32_e32 v155, v155, v156
	v_add_f32_e32 v154, v154, v155
	v_mul_f32_e32 v155, v121, v121
	v_mul_f32_e32 v156, v123, v123
	v_fmac_f32_e32 v155, v120, v120
	v_fmac_f32_e32 v156, v122, v122
	v_add_f32_e32 v155, v155, v156
	v_add_f32_e32 v154, v154, v155
	v_mul_f32_e32 v155, v125, v125
	v_mul_f32_e32 v156, v127, v127
	v_fmac_f32_e32 v155, v124, v124
	v_fmac_f32_e32 v156, v126, v126
	v_add_f32_e32 v155, v155, v156
	v_add_f32_e32 v154, v154, v155
	v_cvt_pk_bf16_f32 v112, v112, v113
	v_cvt_pk_bf16_f32 v113, v114, v115
	v_cvt_pk_bf16_f32 v116, v116, v117
	v_cvt_pk_bf16_f32 v117, v118, v119
	v_cvt_pk_bf16_f32 v120, v120, v121
	v_cvt_pk_bf16_f32 v121, v122, v123
	v_cvt_pk_bf16_f32 v124, v124, v125
	v_cvt_pk_bf16_f32 v125, v126, v127
	v_add_u32_e32 v157, s42, v189
	s_lshl_b32 s90, s43, 7
	v_lshlrev_b32_e32 v158, 11, v157
	v_add3_u32 v158, v158, s90, v233
	v_mov_b32_e32 v160, v112
	v_mov_b32_e32 v161, v113
	v_mov_b32_e32 v162, v116
	v_mov_b32_e32 v163, v117
	s_nop 1
	v_permlane16_swap_b32_e32 v160, v162
	v_permlane16_swap_b32_e32 v161, v163
	s_nop 1
	global_store_dwordx4 v158, v[160:163], s[48:49] offset:0
	s_nop 1
	v_mov_b32_e32 v160, v120
	v_mov_b32_e32 v161, v121
	v_mov_b32_e32 v162, v124
	v_mov_b32_e32 v163, v125
	s_nop 1
	v_permlane16_swap_b32_e32 v160, v162
	v_permlane16_swap_b32_e32 v161, v163
	s_nop 1
	global_store_dwordx4 v158, v[160:163], s[48:49] offset:64
	s_nop 1
	v_mov_b32_e32 v155, v154
	s_nop 1
	v_permlane16_swap_b32_e32 v154, v155
	v_add_f32_e32 v154, v154, v155
	v_mov_b32_e32 v155, v154
	s_nop 1
	v_permlane32_swap_b32_e32 v154, v155
	v_add_f32_e32 v154, v154, v155
	v_mul_u32_u24_e32 v157, 48, v157
	s_lshl_b32 s90, s43, 2
	v_add_u32_e32 v157, s90, v157
	s_and_saveexec_b64 s[80:81], s[74:75]
	global_store_dword v157, v154, s[50:51]
	s_mov_b64 exec, s[80:81]
	s_waitcnt lgkmcnt(0)
	s_barrier
	s_mov_b32 s90, s14
	s_mov_b32 s91, s15
	s_mov_b32 s92, s16
	s_mov_b32 s93, s12
	s_mov_b32 s97, s13
	s_mov_b32 s12, s90
	s_mov_b32 s13, s91
	s_mov_b32 s14, s92
	s_mov_b32 s15, s93
	s_mov_b32 s16, s97
	s_mov_b64 s[18:19], s[30:31]
	s_mov_b64 s[20:21], s[34:35]
	s_mov_b64 s[24:25], s[36:37]
	s_mov_b32 s38, s39
	s_mov_b32 s40, s41
	s_mov_b32 s42, s44
	s_mov_b32 s43, s45
	s_add_i32 s11, s11, s66
	s_cmpk_lt_u32 s11, 0x900
	s_cbranch_scc1 .Latt_unit
	v_readlane_b32 s0, v244, 20
	s_bfe_u32 s3, s0, 0x20006
